# scan step: all five vector prefetches at the top of the step, one waitcnt per step (33 instead of 35 instructions per step)
# speedup vs baseline: 1.1012x; 1.0215x over previous
; __device__ __forceinline__ void phase_rwkv_scan(const Fr& F, int jr) {
;     ...
;         for (int chunk = 0; chunk < TB / 64; ++chunk) {
; #pragma unroll
;             for (int hh = 0; hh < 2; ++hh) {
;                 const int hk = (ht0 + hh) * 16 + l15;
;                 f32x4 cw = {0.f, 0.f, 0.f, 0.f}, ca = {0.f, 0.f, 0.f, 0.f};
; #pragma unroll
;                 for (int kst = 0; kst < 2; ++kst) { cw = __builtin_amdgcn_mfma_f32_16x16x32_bf16(Aw[kst], Bw[hh][kst], cw, 0, 0, 0); ca = __builtin_amdgcn_mfma_f32_16x16x32_bf16(Aa[kst], Ba[hh][kst], ca, 0, 0, 0); }
.LBB0_556:
	s_cmp_eq_u32 s56, 0
	s_cbranch_scc1 .Lvw_rw0_all
	s_cmp_gt_u32 s68, 3
	s_cbranch_scc1 .Lvw_rw0_all
	s_waitcnt vmcnt(4)
	s_branch .Lvw_rw0_done

; __device__ __forceinline__ float sigm(float x) { return __builtin_amdgcn_rcpf(1.f + __expf(-x)); }
; template <int CTRL> __device__ __forceinline__ float dppf(float x) { return __builtin_bit_cast(float, __builtin_amdgcn_update_dpp(0, __builtin_bit_cast(int, x), CTRL, 0xF, 0xF, false)); }
; #define LDS_BAR() asm volatile("s_waitcnt lgkmcnt(0)\n\ts_barrier" ::: "memory")
; __device__ __forceinline__ void phase_rwkv_scan(const Fr& F, int jr) {
;     ...
;         for (int chunk = 0; chunk < TB / 64; ++chunk) {
; #pragma unroll
;             for (int hh = 0; hh < 2; ++hh) {
;                 const int hk = (ht0 + hh) * 16 + l15;
;                 f32x4 cw = {0.f, 0.f, 0.f, 0.f}, ca = {0.f, 0.f, 0.f, 0.f};
; #pragma unroll
;                 for (int kst = 0; kst < 2; ++kst) { cw = __builtin_amdgcn_mfma_f32_16x16x32_bf16(Aw[kst], Bw[hh][kst], cw, 0, 0, 0); ca = __builtin_amdgcn_mfma_f32_16x16x32_bf16(Aa[kst], Ba[hh][kst], ca, 0, 0, 0); }
; #pragma unroll
;                 for (int reg = 0; reg < 4; ++reg) { const int pp = pt * 16 + lq * 4 + reg;
;                     Wv[pp * 64 + hk] = __expf(-0.60653066f * sigm(w0v[hh] + cw[reg]));
;                     Av[pp * 64 + hk] = sigm(a0v[hh] + ca[reg]); }
;             }
;             LDS_BAR();
;             {
;                 const float kr[8] = {lo_bf(kw.x), hi_bf(kw.x), lo_bf(kw.y), hi_bf(kw.y), lo_bf(kw.z), hi_bf(kw.z), lo_bf(kw.w), hi_bf(kw.w)};
;                 const float rr[8] = {lo_bf(rw.x), hi_bf(rw.x), lo_bf(rw.y), hi_bf(rw.y), lo_bf(rw.z), hi_bf(rw.z), lo_bf(rw.w), hi_bf(rw.w)};
;                 float kq[8]; float ss = 0.f, bon = 0.f;
; #pragma unroll
;                 for (int i = 0; i < 8; ++i) { kq[i] = kr[i] * kkc[i]; ss += kq[i] * kq[i]; bon += rr[i] * kr[i] * rkc[i]; }
;                 ss += dppf<0xB1>(ss); ss += dppf<0x4E>(ss); ss += dppf<0x141>(ss); bon += dppf<0xB1>(bon); bon += dppf<0x4E>(bon); bon += dppf<0x141>(bon);
;                 if (s == 0 && half == 0 && j8 == 0) Bon[((size_t)b * TB + tokof(s, chunk * 64 + p2)) * 16 + h] = bon;
.Lvw_rw0_done:
	v_mfma_f32_16x16x32_bf16 v[80:83], v[56:59], v[0:3], 0
	v_lshlrev_b32_e32 v92, 16, v73
	v_and_b32_e32 v93, 0xffff0000, v73
	v_pk_mul_f32 v[98:99], v[46:47], v[92:93]
	v_mfma_f32_16x16x32_bf16 v[80:83], v[60:63], v[4:7], v[80:83]
	v_mul_f32_e64 v106, v98, v98
	v_mul_f32_e64 v107, v99, v99
	v_and_b32_e32 v91, 0xffff0000, v74
	v_and_b32_e32 v95, 0xffff0000, v75
	v_mfma_f32_16x16x32_bf16 v[84:87], v[64:67], v[8:11], 0
	v_mfma_f32_16x16x32_bf16 v[84:87], v[68:71], v[12:15], v[84:87]
	s_nop 1
	v_add_f32_e32 v80, v193, v80
	v_mul_f32_e32 v80, 0xbfb8aa3b, v80
	v_exp_f32_e32 v80, v80
	v_add_f32_e32 v81, v193, v81
	v_mul_f32_e32 v81, 0xbfb8aa3b, v81
	v_exp_f32_e32 v81, v81
	v_add_f32_e32 v80, 1.0, v80
	v_rcp_f32_e32 v80, v80
	v_add_f32_e32 v84, v194, v84
	v_add_f32_e32 v81, 1.0, v81
	v_rcp_f32_e32 v81, v81
	v_mul_f32_e32 v80, 0xbf1b4598, v80
	v_mul_f32_e32 v80, 0x3fb8aa3b, v80
	v_exp_f32_e32 v80, v80
	v_mul_f32_e32 v81, 0xbf1b4598, v81
	v_mul_f32_e32 v81, 0x3fb8aa3b, v81
	v_add_f32_e32 v83, v193, v83
	ds_write_b32 v178, v80
	v_exp_f32_e32 v80, v81
	v_add_f32_e32 v81, v193, v82
	v_mul_f32_e32 v81, 0xbfb8aa3b, v81
	v_add_f32_e32 v82, v194, v85
	v_exp_f32_e32 v81, v81
	v_mul_f32_e32 v82, 0xbfb8aa3b, v82
	v_exp_f32_e32 v82, v82
	v_mul_f32_e32 v84, 0xbfb8aa3b, v84
	v_add_f32_e32 v81, 1.0, v81
	v_mul_f32_e32 v83, 0xbfb8aa3b, v83
	v_exp_f32_e32 v84, v84
	v_rcp_f32_e32 v81, v81
	ds_write_b32 v178, v80 offset:256
	v_add_f32_e32 v80, 1.0, v82
	v_add_f32_e32 v82, v194, v86
	v_exp_f32_e32 v83, v83
	v_mul_f32_e32 v82, 0xbfb8aa3b, v82
	v_exp_f32_e32 v82, v82
	v_add_f32_e32 v84, 1.0, v84
	v_mul_f32_e32 v81, 0xbf1b4598, v81
	v_add_f32_e32 v83, 1.0, v83
	v_rcp_f32_e32 v84, v84
	v_rcp_f32_e32 v80, v80
	v_mul_f32_e32 v81, 0x3fb8aa3b, v81
	v_rcp_f32_e32 v83, v83
	v_exp_f32_e32 v81, v81
	v_add_f32_e32 v82, 1.0, v82
	v_rcp_f32_e32 v82, v82
	ds_write_b32 v179, v84
	ds_write_b32 v180, v80
	ds_write_b32 v178, v81 offset:512
	ds_write_b32 v181, v82
	v_mul_f32_e32 v80, 0xbf1b4598, v83
	v_mul_f32_e32 v80, 0x3fb8aa3b, v80
	v_exp_f32_e32 v88, v80
	v_mfma_f32_16x16x32_bf16 v[80:83], v[56:59], v[16:19], 0
	v_add_f32_e32 v84, v194, v87
	v_mul_f32_e32 v84, 0xbfb8aa3b, v84
	v_exp_f32_e32 v84, v84
	v_mfma_f32_16x16x32_bf16 v[80:83], v[60:63], v[20:23], v[80:83]
	v_add_f32_e32 v84, 1.0, v84
	v_rcp_f32_e32 v89, v84
	v_mfma_f32_16x16x32_bf16 v[84:87], v[64:67], v[24:27], 0
	s_nop 4
	v_add_f32_e32 v80, v196, v80
	v_mul_f32_e32 v80, 0xbfb8aa3b, v80
	v_exp_f32_e32 v80, v80
	v_mfma_f32_16x16x32_bf16 v[84:87], v[68:71], v[28:31], v[84:87]
	v_add_f32_e32 v81, v196, v81
	v_mul_f32_e32 v81, 0xbfb8aa3b, v81
	v_add_f32_e32 v80, 1.0, v80
	v_rcp_f32_e32 v80, v80
	v_exp_f32_e32 v81, v81
	s_nop 2
	v_add_f32_e32 v84, v195, v84
	v_mul_f32_e32 v84, 0xbfb8aa3b, v84
	v_mul_f32_e32 v80, 0xbf1b4598, v80
	v_mul_f32_e32 v80, 0x3fb8aa3b, v80
	v_exp_f32_e32 v80, v80
	v_exp_f32_e32 v84, v84
	v_add_f32_e32 v82, v196, v82
	v_add_f32_e32 v81, 1.0, v81
	v_mul_f32_e32 v82, 0xbfb8aa3b, v82
	ds_write_b32 v178, v88 offset:768
	ds_write_b32 v182, v89
	v_rcp_f32_e32 v81, v81
	ds_write_b32 v178, v80 offset:64
	v_add_f32_e32 v80, 1.0, v84
	v_add_f32_e32 v84, v195, v85
	v_exp_f32_e32 v82, v82
	v_mul_f32_e32 v84, 0xbfb8aa3b, v84
	v_exp_f32_e32 v84, v84
	v_mul_f32_e32 v81, 0xbf1b4598, v81
	v_add_f32_e32 v82, 1.0, v82
	v_rcp_f32_e32 v80, v80
	v_mul_f32_e32 v81, 0x3fb8aa3b, v81
	v_rcp_f32_e32 v82, v82
	v_exp_f32_e32 v81, v81
	v_add_f32_e32 v84, 1.0, v84
	v_rcp_f32_e32 v84, v84
	ds_write_b32 v183, v80
	ds_write_b32 v184, v81 offset:256
	ds_write_b32 v185, v84
	v_mul_f32_e32 v80, 0xbf1b4598, v82
	v_add_f32_e32 v82, v196, v83
	v_mul_f32_e32 v82, 0xbfb8aa3b, v82
	v_exp_f32_e32 v82, v82
	v_add_f32_e32 v81, v195, v86
	v_mul_f32_e32 v81, 0xbfb8aa3b, v81
	v_exp_f32_e32 v81, v81
	v_add_f32_e32 v82, 1.0, v82
	v_rcp_f32_e32 v82, v82
	v_add_f32_e32 v83, v195, v87
	v_mul_f32_e32 v83, 0xbfb8aa3b, v83
	v_exp_f32_e32 v83, v83
	v_mul_f32_e32 v80, 0x3fb8aa3b, v80
	v_lshlrev_b32_e32 v84, 16, v76
	v_lshlrev_b32_e32 v88, 16, v72
	v_exp_f32_e32 v80, v80
	v_add_f32_e32 v81, 1.0, v81
	v_mul_f32_e32 v82, 0xbf1b4598, v82
	v_and_b32_e32 v85, 0xffff0000, v76
	v_and_b32_e32 v89, 0xffff0000, v72
	v_mul_f32_e32 v90, v88, v84
	v_rcp_f32_e32 v81, v81
	v_mul_f32_e32 v82, 0x3fb8aa3b, v82
	v_lshlrev_b32_e32 v86, 16, v77
	v_fma_f32 v112, v32, v90, 0
	v_mul_f32_e32 v90, v89, v85
	v_exp_f32_e32 v82, v82
	v_add_f32_e32 v83, 1.0, v83
	v_and_b32_e32 v87, 0xffff0000, v77
	v_fmac_f32_e32 v112, v33, v90
	v_mul_f32_e32 v90, v92, v86
	v_rcp_f32_e32 v83, v83
	v_pk_mul_f32 v[96:97], v[44:45], v[88:89]
	v_fmac_f32_e32 v112, v34, v90
	v_mul_f32_e32 v90, v93, v87
	ds_write_b32 v184, v80 offset:512
	ds_write_b32 v186, v81
	ds_write_b32 v184, v82 offset:768
	ds_write_b32 v187, v83
	v_lshlrev_b32_e32 v80, 16, v78
	v_pk_mul_f32 v[104:105], v[96:97], v[96:97]
	v_fmac_f32_e32 v112, v35, v90
	v_lshlrev_b32_e32 v90, 16, v74
	v_and_b32_e32 v81, 0xffff0000, v78
	v_mul_f32_e32 v94, v90, v80
	v_add_f32_e32 v104, v104, v105
	v_pk_mul_f32 v[100:101], v[40:41], v[90:91]
	v_fmac_f32_e32 v112, v36, v94
	v_mul_f32_e32 v94, v91, v81
	v_add_f32_e32 v104, v106, v104
	v_pk_mul_f32 v[108:109], v[100:101], v[100:101]
	v_fmac_f32_e32 v112, v37, v94
	v_lshlrev_b32_e32 v94, 16, v75
	v_add_f32_e32 v104, v107, v104
	v_lshlrev_b32_e32 v82, 16, v79
	v_pk_mul_f32 v[102:103], v[42:43], v[94:95]
	v_add_f32_e32 v104, v108, v104
	v_and_b32_e32 v83, 0xffff0000, v79
	v_pk_mul_f32 v[110:111], v[102:103], v[102:103]
	v_mul_f32_e32 v113, v94, v82
	v_add_f32_e32 v104, v109, v104
	v_fmac_f32_e32 v112, v38, v113
	v_add_f32_e32 v104, v110, v104
	v_mul_f32_e32 v105, v95, v83
	v_add_f32_e32 v104, v111, v104
	v_fmac_f32_e32 v112, v39, v105
	s_waitcnt lgkmcnt(0)
	s_barrier
	v_mov_b32_e32 v105, 0
	v_add_f32_dpp v104, v104, v104 quad_perm:[1,0,3,2] row_mask:0xf bank_mask:0xf bound_ctrl:1
	v_add_f32_dpp v106, v112, v112 quad_perm:[1,0,3,2] row_mask:0xf bank_mask:0xf bound_ctrl:1
	v_mov_b32_e32 v107, 0
	v_add_f32_dpp v104, v104, v104 quad_perm:[2,3,0,1] row_mask:0xf bank_mask:0xf bound_ctrl:1
	v_add_f32_dpp v106, v106, v106 quad_perm:[2,3,0,1] row_mask:0xf bank_mask:0xf bound_ctrl:1
	s_nop 0
	v_mov_b32_dpp v105, v104 row_half_mirror row_mask:0xf bank_mask:0xf
	v_mov_b32_dpp v107, v106 row_half_mirror row_mask:0xf bank_mask:0xf
	s_and_saveexec_b64 s[10:11], s[8:9]
	s_cbranch_execz .LBB0_558
	v_lshl_add_u32 v122, s56, 6, v147
	v_add_f32_e32 v108, v106, v107
	v_lshlrev_b64 v[106:107], 6, v[122:123]
	v_lshl_add_u64 v[106:107], s[46:47], 0, v[106:107]
	global_store_dword v[106:107], v108, off

; template <int CTRL> __device__ __forceinline__ float dppf(float x) { return __builtin_bit_cast(float, __builtin_amdgcn_update_dpp(0, __builtin_bit_cast(int, x), CTRL, 0xF, 0xF, false)); }
; __device__ __forceinline__ void phase_rwkv_scan(const Fr& F, int jr) {
;     ...
;                 for (int pg = 0; pg < 64; pg += 16) {
; #pragma unroll
;                     for (int pi = 0; pi < 16; ++pi) {
;                         const int p = pg + pi, pn = p < 63 ? p + 1 : 63;
;                         const f32x4 w4n = PW[pn * 16], k4n = PW[1024 + pn * 16], b4n = PW[2048 + pn * 16], d4n = PW[3072 + pn * 16], r4n = PR[pn * 16];
;                         const float vvn = PV[pn * 32];
;                         f32x2 t = S01 * k4.xy; t = S23 * k4.zw + t; float sa = t.x + t.y;
;                         sa += dppf<0x128>(sa);
;                         const f32x2 dv01 = d4.xy * vv, dv23 = d4.zw * vv;
;                         sa += dppf<0x124>(sa);
;                         const f32x2 e01 = S01 * w4.xy + dv01;
;                         sa += dppf<0x122>(sa);
;                         const f32x2 e23 = S23 * w4.zw + dv23;
;                         sa += dppf<0x121>(sa);
;                         S01 = e01 - b4.xy * sa; S23 = e23 - b4.zw * sa;
;                         f32x2 u = S01 * r4.xy; u = S23 * r4.zw + u;
;                         PY[pi * 64] = u.x + u.y;
;                         w4 = w4n; k4 = k4n; b4 = b4n; d4 = d4n; r4 = r4n; vv = vvn;
;                     }
.Lrw0_group:
	ds_read_b128 v[106:109], v240 offset:16640
	ds_read_b64 v[118:119], v242 offset:256
	ds_read_b128 v[114:117], v240 offset:49408
	ds_read_b128 v[102:105], v240 offset:256
	ds_read_b128 v[110:113], v240 offset:33024
	v_pk_mul_f32 v[226:227], v[206:207], v[84:85] op_sel_hi:[1,0]
	v_pk_mul_f32 v[232:233], v[100:101], v[92:93] op_sel_hi:[1,0]
	v_pk_fma_f32 v[226:227], v[208:209], v[84:85], v[226:227] op_sel:[0,1,0]
	v_pk_mul_f32 v[234:235], v[100:101], v[92:93] op_sel:[0,1]
	v_pk_fma_f32 v[226:227], v[210:211], v[86:87], v[226:227] op_sel_hi:[1,0,1]
	v_pk_mul_f32 v[236:237], v[100:101], v[94:95] op_sel_hi:[1,0]
	v_pk_fma_f32 v[226:227], v[212:213], v[86:87], v[226:227] op_sel:[0,1,0]
	v_pk_mul_f32 v[238:239], v[100:101], v[94:95] op_sel:[0,1]
	s_nop 0
	v_add_f32_dpp v230, v227, v226 row_ror:8 row_mask:0xf bank_mask:0xf
	v_pk_fma_f32 v[232:233], v[206:207], v[80:81], v[232:233] op_sel_hi:[1,0,1]
	v_pk_fma_f32 v[234:235], v[208:209], v[80:81], v[234:235] op_sel:[0,1,0]
	v_add_f32_dpp v230, v230, v230 quad_perm:[1,0,3,2] row_mask:0xf bank_mask:0xf
	v_pk_fma_f32 v[236:237], v[210:211], v[82:83], v[236:237] op_sel_hi:[1,0,1]
	v_pk_fma_f32 v[238:239], v[212:213], v[82:83], v[238:239] op_sel:[0,1,0]
	v_add_f32_dpp v230, v230, v230 quad_perm:[2,3,0,1] row_mask:0xf bank_mask:0xf
	ds_read_b128 v[222:225], v241 offset:256
	s_nop 0
	v_add_f32_dpp v230, v230, v230 row_half_mirror row_mask:0xf bank_mask:0xf
	s_nop 1
	v_mov_b32_dpp v231, v230 row_ror:8 row_mask:0xf bank_mask:0xf
	s_nop 0
	v_pk_fma_f32 v[206:207], v[88:89], v[230:231], v[232:233] op_sel_hi:[0,1,1] neg_lo:[1,0,0] neg_hi:[1,0,0]
	v_pk_fma_f32 v[208:209], v[88:89], v[230:231], v[234:235] op_sel:[1,0,0] neg_lo:[1,0,0] neg_hi:[1,0,0]
	v_pk_fma_f32 v[210:211], v[90:91], v[230:231], v[236:237] op_sel_hi:[0,1,1] neg_lo:[1,0,0] neg_hi:[1,0,0]
	v_pk_fma_f32 v[212:213], v[90:91], v[230:231], v[238:239] op_sel:[1,0,0] neg_lo:[1,0,0] neg_hi:[1,0,0]
	ds_read_b128 v[84:87], v240 offset:16896
	ds_read_b64 v[100:101], v242 offset:512
	ds_read_b128 v[92:95], v240 offset:49664
	ds_read_b128 v[80:83], v240 offset:512
	ds_read_b128 v[88:91], v240 offset:33280
	s_waitcnt lgkmcnt(6)
	v_pk_mul_f32 v[226:227], v[206:207], v[106:107] op_sel_hi:[1,0]
	v_pk_mul_f32 v[228:229], v[206:207], v[96:97] op_sel_hi:[1,0]
	v_pk_fma_f32 v[226:227], v[208:209], v[106:107], v[226:227] op_sel:[0,1,0]
	v_pk_fma_f32 v[228:229], v[208:209], v[96:97], v[228:229] op_sel:[0,1,0]
	v_pk_fma_f32 v[226:227], v[210:211], v[108:109], v[226:227] op_sel_hi:[1,0,1]
	v_pk_fma_f32 v[228:229], v[210:211], v[98:99], v[228:229] op_sel_hi:[1,0,1]
	v_pk_fma_f32 v[226:227], v[212:213], v[108:109], v[226:227] op_sel:[0,1,0]
	v_pk_fma_f32 v[228:229], v[212:213], v[98:99], v[228:229] op_sel:[0,1,0]
	v_pk_mul_f32 v[232:233], v[118:119], v[114:115] op_sel_hi:[1,0]
	v_add_f32_dpp v230, v227, v226 row_ror:8 row_mask:0xf bank_mask:0xf
	v_pk_mul_f32 v[234:235], v[118:119], v[114:115] op_sel:[0,1]
	v_pk_mul_f32 v[236:237], v[118:119], v[116:117] op_sel_hi:[1,0]
	v_add_f32_dpp v230, v230, v230 quad_perm:[1,0,3,2] row_mask:0xf bank_mask:0xf
	v_pk_mul_f32 v[238:239], v[118:119], v[116:117] op_sel:[0,1]
	ds_read_b128 v[96:99], v241 offset:512
	v_add_f32_dpp v230, v230, v230 quad_perm:[2,3,0,1] row_mask:0xf bank_mask:0xf
	v_pk_fma_f32 v[232:233], v[206:207], v[102:103], v[232:233] op_sel_hi:[1,0,1]
	v_pk_fma_f32 v[234:235], v[208:209], v[102:103], v[234:235] op_sel:[0,1,0]
	v_add_f32_dpp v230, v230, v230 row_half_mirror row_mask:0xf bank_mask:0xf
	v_pk_fma_f32 v[236:237], v[210:211], v[104:105], v[236:237] op_sel_hi:[1,0,1]
	v_pk_fma_f32 v[238:239], v[212:213], v[104:105], v[238:239] op_sel:[0,1,0]
	v_mov_b32_dpp v231, v230 row_ror:8 row_mask:0xf bank_mask:0xf
	ds_write_b64 v217, v[228:229] offset:0
	v_pk_fma_f32 v[206:207], v[110:111], v[230:231], v[232:233] op_sel_hi:[0,1,1] neg_lo:[1,0,0] neg_hi:[1,0,0]
	v_pk_fma_f32 v[208:209], v[110:111], v[230:231], v[234:235] op_sel:[1,0,0] neg_lo:[1,0,0] neg_hi:[1,0,0]
	v_pk_fma_f32 v[210:211], v[112:113], v[230:231], v[236:237] op_sel_hi:[0,1,1] neg_lo:[1,0,0] neg_hi:[1,0,0]
	v_pk_fma_f32 v[212:213], v[112:113], v[230:231], v[238:239] op_sel:[1,0,0] neg_lo:[1,0,0] neg_hi:[1,0,0]
	ds_read_b128 v[106:109], v240 offset:17152
	ds_read_b64 v[118:119], v242 offset:768
	ds_read_b128 v[114:117], v240 offset:49920
	ds_read_b128 v[102:105], v240 offset:768
	ds_read_b128 v[110:113], v240 offset:33536
	s_waitcnt lgkmcnt(7)
	v_pk_mul_f32 v[226:227], v[206:207], v[84:85] op_sel_hi:[1,0]
	v_pk_mul_f32 v[228:229], v[206:207], v[222:223] op_sel_hi:[1,0]
	v_pk_fma_f32 v[226:227], v[208:209], v[84:85], v[226:227] op_sel:[0,1,0]
	v_pk_fma_f32 v[228:229], v[208:209], v[222:223], v[228:229] op_sel:[0,1,0]
	v_pk_fma_f32 v[226:227], v[210:211], v[86:87], v[226:227] op_sel_hi:[1,0,1]
	v_pk_fma_f32 v[228:229], v[210:211], v[224:225], v[228:229] op_sel_hi:[1,0,1]
	v_pk_fma_f32 v[226:227], v[212:213], v[86:87], v[226:227] op_sel:[0,1,0]
	v_pk_fma_f32 v[228:229], v[212:213], v[224:225], v[228:229] op_sel:[0,1,0]
	v_pk_mul_f32 v[232:233], v[100:101], v[92:93] op_sel_hi:[1,0]
	v_add_f32_dpp v230, v227, v226 row_ror:8 row_mask:0xf bank_mask:0xf
	v_pk_mul_f32 v[234:235], v[100:101], v[92:93] op_sel:[0,1]
	v_pk_mul_f32 v[236:237], v[100:101], v[94:95] op_sel_hi:[1,0]
	v_add_f32_dpp v230, v230, v230 quad_perm:[1,0,3,2] row_mask:0xf bank_mask:0xf
	v_pk_mul_f32 v[238:239], v[100:101], v[94:95] op_sel:[0,1]
	ds_read_b128 v[222:225], v241 offset:768
	v_add_f32_dpp v230, v230, v230 quad_perm:[2,3,0,1] row_mask:0xf bank_mask:0xf
	v_pk_fma_f32 v[232:233], v[206:207], v[80:81], v[232:233] op_sel_hi:[1,0,1]
	v_pk_fma_f32 v[234:235], v[208:209], v[80:81], v[234:235] op_sel:[0,1,0]
	v_add_f32_dpp v230, v230, v230 row_half_mirror row_mask:0xf bank_mask:0xf
	v_pk_fma_f32 v[236:237], v[210:211], v[82:83], v[236:237] op_sel_hi:[1,0,1]
	v_pk_fma_f32 v[238:239], v[212:213], v[82:83], v[238:239] op_sel:[0,1,0]
	v_mov_b32_dpp v231, v230 row_ror:8 row_mask:0xf bank_mask:0xf
	ds_write_b64 v217, v[228:229] offset:576
	v_pk_fma_f32 v[206:207], v[88:89], v[230:231], v[232:233] op_sel_hi:[0,1,1] neg_lo:[1,0,0] neg_hi:[1,0,0]
	v_pk_fma_f32 v[208:209], v[88:89], v[230:231], v[234:235] op_sel:[1,0,0] neg_lo:[1,0,0] neg_hi:[1,0,0]
	v_pk_fma_f32 v[210:211], v[90:91], v[230:231], v[236:237] op_sel_hi:[0,1,1] neg_lo:[1,0,0] neg_hi:[1,0,0]
	v_pk_fma_f32 v[212:213], v[90:91], v[230:231], v[238:239] op_sel:[1,0,0] neg_lo:[1,0,0] neg_hi:[1,0,0]
	ds_read_b128 v[84:87], v240 offset:17408
	ds_read_b64 v[100:101], v242 offset:1024
	ds_read_b128 v[92:95], v240 offset:50176
	ds_read_b128 v[80:83], v240 offset:1024
	ds_read_b128 v[88:91], v240 offset:33792
	s_waitcnt lgkmcnt(7)
; template <int CTRL> __device__ __forceinline__ float dppf(float x) { return __builtin_bit_cast(float, __builtin_amdgcn_update_dpp(0, __builtin_bit_cast(int, x), CTRL, 0xF, 0xF, false)); }
; __device__ __forceinline__ void phase_rwkv_scan(const Fr& F, int jr) {
;     ...
;                 for (int pg = 0; pg < 64; pg += 16) {
; #pragma unroll
;                     for (int pi = 0; pi < 16; ++pi) {
;                         const int p = pg + pi, pn = p < 63 ? p + 1 : 63;
;                         const f32x4 w4n = PW[pn * 16], k4n = PW[1024 + pn * 16], b4n = PW[2048 + pn * 16], d4n = PW[3072 + pn * 16], r4n = PR[pn * 16];
;                         const float vvn = PV[pn * 32];
;                         f32x2 t = S01 * k4.xy; t = S23 * k4.zw + t; float sa = t.x + t.y;
;                         sa += dppf<0x128>(sa);
;                         const f32x2 dv01 = d4.xy * vv, dv23 = d4.zw * vv;
;                         sa += dppf<0x124>(sa);
;                         const f32x2 e01 = S01 * w4.xy + dv01;
;                         sa += dppf<0x122>(sa);
;                         const f32x2 e23 = S23 * w4.zw + dv23;
;                         sa += dppf<0x121>(sa);
;                         S01 = e01 - b4.xy * sa; S23 = e23 - b4.zw * sa;
;                         f32x2 u = S01 * r4.xy; u = S23 * r4.zw + u;
;                         PY[pi * 64] = u.x + u.y;
;                         w4 = w4n; k4 = k4n; b4 = b4n; d4 = d4n; r4 = r4n; vv = vvn;
;                     }
	v_pk_mul_f32 v[226:227], v[206:207], v[106:107] op_sel_hi:[1,0]
	v_pk_mul_f32 v[228:229], v[206:207], v[96:97] op_sel_hi:[1,0]
	v_pk_fma_f32 v[226:227], v[208:209], v[106:107], v[226:227] op_sel:[0,1,0]
	v_pk_fma_f32 v[228:229], v[208:209], v[96:97], v[228:229] op_sel:[0,1,0]
	v_pk_fma_f32 v[226:227], v[210:211], v[108:109], v[226:227] op_sel_hi:[1,0,1]
	v_pk_fma_f32 v[228:229], v[210:211], v[98:99], v[228:229] op_sel_hi:[1,0,1]
	v_pk_fma_f32 v[226:227], v[212:213], v[108:109], v[226:227] op_sel:[0,1,0]
	v_pk_fma_f32 v[228:229], v[212:213], v[98:99], v[228:229] op_sel:[0,1,0]
	v_pk_mul_f32 v[232:233], v[118:119], v[114:115] op_sel_hi:[1,0]
	v_add_f32_dpp v230, v227, v226 row_ror:8 row_mask:0xf bank_mask:0xf
	v_pk_mul_f32 v[234:235], v[118:119], v[114:115] op_sel:[0,1]
	v_pk_mul_f32 v[236:237], v[118:119], v[116:117] op_sel_hi:[1,0]
	v_add_f32_dpp v230, v230, v230 quad_perm:[1,0,3,2] row_mask:0xf bank_mask:0xf
	v_pk_mul_f32 v[238:239], v[118:119], v[116:117] op_sel:[0,1]
	ds_read_b128 v[96:99], v241 offset:1024
	v_add_f32_dpp v230, v230, v230 quad_perm:[2,3,0,1] row_mask:0xf bank_mask:0xf
	v_pk_fma_f32 v[232:233], v[206:207], v[102:103], v[232:233] op_sel_hi:[1,0,1]
	v_pk_fma_f32 v[234:235], v[208:209], v[102:103], v[234:235] op_sel:[0,1,0]
	v_add_f32_dpp v230, v230, v230 row_half_mirror row_mask:0xf bank_mask:0xf
	v_pk_fma_f32 v[236:237], v[210:211], v[104:105], v[236:237] op_sel_hi:[1,0,1]
	v_pk_fma_f32 v[238:239], v[212:213], v[104:105], v[238:239] op_sel:[0,1,0]
	v_mov_b32_dpp v231, v230 row_ror:8 row_mask:0xf bank_mask:0xf
	ds_write_b64 v217, v[228:229] offset:1152
	v_pk_fma_f32 v[206:207], v[110:111], v[230:231], v[232:233] op_sel_hi:[0,1,1] neg_lo:[1,0,0] neg_hi:[1,0,0]
	v_pk_fma_f32 v[208:209], v[110:111], v[230:231], v[234:235] op_sel:[1,0,0] neg_lo:[1,0,0] neg_hi:[1,0,0]
	v_pk_fma_f32 v[210:211], v[112:113], v[230:231], v[236:237] op_sel_hi:[0,1,1] neg_lo:[1,0,0] neg_hi:[1,0,0]
	v_pk_fma_f32 v[212:213], v[112:113], v[230:231], v[238:239] op_sel:[1,0,0] neg_lo:[1,0,0] neg_hi:[1,0,0]
	ds_read_b128 v[106:109], v240 offset:17664
	ds_read_b64 v[118:119], v242 offset:1280
	ds_read_b128 v[114:117], v240 offset:50432
	ds_read_b128 v[102:105], v240 offset:1280
	ds_read_b128 v[110:113], v240 offset:34048
	s_waitcnt lgkmcnt(7)
	v_pk_mul_f32 v[226:227], v[206:207], v[84:85] op_sel_hi:[1,0]
	v_pk_mul_f32 v[228:229], v[206:207], v[222:223] op_sel_hi:[1,0]
	v_pk_fma_f32 v[226:227], v[208:209], v[84:85], v[226:227] op_sel:[0,1,0]
	v_pk_fma_f32 v[228:229], v[208:209], v[222:223], v[228:229] op_sel:[0,1,0]
	v_pk_fma_f32 v[226:227], v[210:211], v[86:87], v[226:227] op_sel_hi:[1,0,1]
	v_pk_fma_f32 v[228:229], v[210:211], v[224:225], v[228:229] op_sel_hi:[1,0,1]
	v_pk_fma_f32 v[226:227], v[212:213], v[86:87], v[226:227] op_sel:[0,1,0]
	v_pk_fma_f32 v[228:229], v[212:213], v[224:225], v[228:229] op_sel:[0,1,0]
	v_pk_mul_f32 v[232:233], v[100:101], v[92:93] op_sel_hi:[1,0]
	v_add_f32_dpp v230, v227, v226 row_ror:8 row_mask:0xf bank_mask:0xf
	v_pk_mul_f32 v[234:235], v[100:101], v[92:93] op_sel:[0,1]
	v_pk_mul_f32 v[236:237], v[100:101], v[94:95] op_sel_hi:[1,0]
	v_add_f32_dpp v230, v230, v230 quad_perm:[1,0,3,2] row_mask:0xf bank_mask:0xf
	v_pk_mul_f32 v[238:239], v[100:101], v[94:95] op_sel:[0,1]
	ds_read_b128 v[222:225], v241 offset:1280
	v_add_f32_dpp v230, v230, v230 quad_perm:[2,3,0,1] row_mask:0xf bank_mask:0xf
	v_pk_fma_f32 v[232:233], v[206:207], v[80:81], v[232:233] op_sel_hi:[1,0,1]
	v_pk_fma_f32 v[234:235], v[208:209], v[80:81], v[234:235] op_sel:[0,1,0]
	v_add_f32_dpp v230, v230, v230 row_half_mirror row_mask:0xf bank_mask:0xf
	v_pk_fma_f32 v[236:237], v[210:211], v[82:83], v[236:237] op_sel_hi:[1,0,1]
	v_pk_fma_f32 v[238:239], v[212:213], v[82:83], v[238:239] op_sel:[0,1,0]
	v_mov_b32_dpp v231, v230 row_ror:8 row_mask:0xf bank_mask:0xf
	ds_write_b64 v217, v[228:229] offset:1728
	v_pk_fma_f32 v[206:207], v[88:89], v[230:231], v[232:233] op_sel_hi:[0,1,1] neg_lo:[1,0,0] neg_hi:[1,0,0]
	v_pk_fma_f32 v[208:209], v[88:89], v[230:231], v[234:235] op_sel:[1,0,0] neg_lo:[1,0,0] neg_hi:[1,0,0]
	v_pk_fma_f32 v[210:211], v[90:91], v[230:231], v[236:237] op_sel_hi:[0,1,1] neg_lo:[1,0,0] neg_hi:[1,0,0]
	v_pk_fma_f32 v[212:213], v[90:91], v[230:231], v[238:239] op_sel:[1,0,0] neg_lo:[1,0,0] neg_hi:[1,0,0]
	ds_read_b128 v[84:87], v240 offset:17920
	ds_read_b64 v[100:101], v242 offset:1536
	ds_read_b128 v[92:95], v240 offset:50688
	ds_read_b128 v[80:83], v240 offset:1536
	ds_read_b128 v[88:91], v240 offset:34304
	s_waitcnt lgkmcnt(7)
	v_pk_mul_f32 v[226:227], v[206:207], v[106:107] op_sel_hi:[1,0]
	v_pk_mul_f32 v[228:229], v[206:207], v[96:97] op_sel_hi:[1,0]
	v_pk_fma_f32 v[226:227], v[208:209], v[106:107], v[226:227] op_sel:[0,1,0]
	v_pk_fma_f32 v[228:229], v[208:209], v[96:97], v[228:229] op_sel:[0,1,0]
	v_pk_fma_f32 v[226:227], v[210:211], v[108:109], v[226:227] op_sel_hi:[1,0,1]
	v_pk_fma_f32 v[228:229], v[210:211], v[98:99], v[228:229] op_sel_hi:[1,0,1]
	v_pk_fma_f32 v[226:227], v[212:213], v[108:109], v[226:227] op_sel:[0,1,0]
	v_pk_fma_f32 v[228:229], v[212:213], v[98:99], v[228:229] op_sel:[0,1,0]
	v_pk_mul_f32 v[232:233], v[118:119], v[114:115] op_sel_hi:[1,0]
	v_add_f32_dpp v230, v227, v226 row_ror:8 row_mask:0xf bank_mask:0xf
	v_pk_mul_f32 v[234:235], v[118:119], v[114:115] op_sel:[0,1]
	v_pk_mul_f32 v[236:237], v[118:119], v[116:117] op_sel_hi:[1,0]
	v_add_f32_dpp v230, v230, v230 quad_perm:[1,0,3,2] row_mask:0xf bank_mask:0xf
	v_pk_mul_f32 v[238:239], v[118:119], v[116:117] op_sel:[0,1]
	ds_read_b128 v[96:99], v241 offset:1536
	v_add_f32_dpp v230, v230, v230 quad_perm:[2,3,0,1] row_mask:0xf bank_mask:0xf
	v_pk_fma_f32 v[232:233], v[206:207], v[102:103], v[232:233] op_sel_hi:[1,0,1]
	v_pk_fma_f32 v[234:235], v[208:209], v[102:103], v[234:235] op_sel:[0,1,0]
	v_add_f32_dpp v230, v230, v230 row_half_mirror row_mask:0xf bank_mask:0xf
	v_pk_fma_f32 v[236:237], v[210:211], v[104:105], v[236:237] op_sel_hi:[1,0,1]
	v_pk_fma_f32 v[238:239], v[212:213], v[104:105], v[238:239] op_sel:[0,1,0]
	v_mov_b32_dpp v231, v230 row_ror:8 row_mask:0xf bank_mask:0xf
	ds_write_b64 v217, v[228:229] offset:2304
	v_pk_fma_f32 v[206:207], v[110:111], v[230:231], v[232:233] op_sel_hi:[0,1,1] neg_lo:[1,0,0] neg_hi:[1,0,0]
	v_pk_fma_f32 v[208:209], v[110:111], v[230:231], v[234:235] op_sel:[1,0,0] neg_lo:[1,0,0] neg_hi:[1,0,0]
	v_pk_fma_f32 v[210:211], v[112:113], v[230:231], v[236:237] op_sel_hi:[0,1,1] neg_lo:[1,0,0] neg_hi:[1,0,0]
	v_pk_fma_f32 v[212:213], v[112:113], v[230:231], v[238:239] op_sel:[1,0,0] neg_lo:[1,0,0] neg_hi:[1,0,0]
	ds_read_b128 v[106:109], v240 offset:18176
	ds_read_b64 v[118:119], v242 offset:1792
	ds_read_b128 v[114:117], v240 offset:50944
	ds_read_b128 v[102:105], v240 offset:1792
	ds_read_b128 v[110:113], v240 offset:34560
	s_waitcnt lgkmcnt(7)
; template <int CTRL> __device__ __forceinline__ float dppf(float x) { return __builtin_bit_cast(float, __builtin_amdgcn_update_dpp(0, __builtin_bit_cast(int, x), CTRL, 0xF, 0xF, false)); }
; __device__ __forceinline__ void phase_rwkv_scan(const Fr& F, int jr) {
;     ...
;                 for (int pg = 0; pg < 64; pg += 16) {
; #pragma unroll
;                     for (int pi = 0; pi < 16; ++pi) {
;                         const int p = pg + pi, pn = p < 63 ? p + 1 : 63;
;                         const f32x4 w4n = PW[pn * 16], k4n = PW[1024 + pn * 16], b4n = PW[2048 + pn * 16], d4n = PW[3072 + pn * 16], r4n = PR[pn * 16];
;                         const float vvn = PV[pn * 32];
;                         f32x2 t = S01 * k4.xy; t = S23 * k4.zw + t; float sa = t.x + t.y;
;                         sa += dppf<0x128>(sa);
;                         const f32x2 dv01 = d4.xy * vv, dv23 = d4.zw * vv;
;                         sa += dppf<0x124>(sa);
;                         const f32x2 e01 = S01 * w4.xy + dv01;
;                         sa += dppf<0x122>(sa);
;                         const f32x2 e23 = S23 * w4.zw + dv23;
;                         sa += dppf<0x121>(sa);
;                         S01 = e01 - b4.xy * sa; S23 = e23 - b4.zw * sa;
;                         f32x2 u = S01 * r4.xy; u = S23 * r4.zw + u;
;                         PY[pi * 64] = u.x + u.y;
;                         w4 = w4n; k4 = k4n; b4 = b4n; d4 = d4n; r4 = r4n; vv = vvn;
;                     }
	v_pk_mul_f32 v[226:227], v[206:207], v[84:85] op_sel_hi:[1,0]
	v_pk_mul_f32 v[228:229], v[206:207], v[222:223] op_sel_hi:[1,0]
	v_pk_fma_f32 v[226:227], v[208:209], v[84:85], v[226:227] op_sel:[0,1,0]
	v_pk_fma_f32 v[228:229], v[208:209], v[222:223], v[228:229] op_sel:[0,1,0]
	v_pk_fma_f32 v[226:227], v[210:211], v[86:87], v[226:227] op_sel_hi:[1,0,1]
	v_pk_fma_f32 v[228:229], v[210:211], v[224:225], v[228:229] op_sel_hi:[1,0,1]
	v_pk_fma_f32 v[226:227], v[212:213], v[86:87], v[226:227] op_sel:[0,1,0]
	v_pk_fma_f32 v[228:229], v[212:213], v[224:225], v[228:229] op_sel:[0,1,0]
	v_pk_mul_f32 v[232:233], v[100:101], v[92:93] op_sel_hi:[1,0]
	v_add_f32_dpp v230, v227, v226 row_ror:8 row_mask:0xf bank_mask:0xf
	v_pk_mul_f32 v[234:235], v[100:101], v[92:93] op_sel:[0,1]
	v_pk_mul_f32 v[236:237], v[100:101], v[94:95] op_sel_hi:[1,0]
	v_add_f32_dpp v230, v230, v230 quad_perm:[1,0,3,2] row_mask:0xf bank_mask:0xf
	v_pk_mul_f32 v[238:239], v[100:101], v[94:95] op_sel:[0,1]
	ds_read_b128 v[222:225], v241 offset:1792
	v_add_f32_dpp v230, v230, v230 quad_perm:[2,3,0,1] row_mask:0xf bank_mask:0xf
	v_pk_fma_f32 v[232:233], v[206:207], v[80:81], v[232:233] op_sel_hi:[1,0,1]
	v_pk_fma_f32 v[234:235], v[208:209], v[80:81], v[234:235] op_sel:[0,1,0]
	v_add_f32_dpp v230, v230, v230 row_half_mirror row_mask:0xf bank_mask:0xf
	v_pk_fma_f32 v[236:237], v[210:211], v[82:83], v[236:237] op_sel_hi:[1,0,1]
	v_pk_fma_f32 v[238:239], v[212:213], v[82:83], v[238:239] op_sel:[0,1,0]
	v_mov_b32_dpp v231, v230 row_ror:8 row_mask:0xf bank_mask:0xf
	ds_write_b64 v217, v[228:229] offset:2880
	v_pk_fma_f32 v[206:207], v[88:89], v[230:231], v[232:233] op_sel_hi:[0,1,1] neg_lo:[1,0,0] neg_hi:[1,0,0]
	v_pk_fma_f32 v[208:209], v[88:89], v[230:231], v[234:235] op_sel:[1,0,0] neg_lo:[1,0,0] neg_hi:[1,0,0]
	v_pk_fma_f32 v[210:211], v[90:91], v[230:231], v[236:237] op_sel_hi:[0,1,1] neg_lo:[1,0,0] neg_hi:[1,0,0]
	v_pk_fma_f32 v[212:213], v[90:91], v[230:231], v[238:239] op_sel:[1,0,0] neg_lo:[1,0,0] neg_hi:[1,0,0]
	ds_read_b128 v[84:87], v240 offset:18432
	ds_read_b64 v[100:101], v242 offset:2048
	ds_read_b128 v[92:95], v240 offset:51200
	ds_read_b128 v[80:83], v240 offset:2048
	ds_read_b128 v[88:91], v240 offset:34816
	s_waitcnt lgkmcnt(7)
	v_pk_mul_f32 v[226:227], v[206:207], v[106:107] op_sel_hi:[1,0]
	v_pk_mul_f32 v[228:229], v[206:207], v[96:97] op_sel_hi:[1,0]
	v_pk_fma_f32 v[226:227], v[208:209], v[106:107], v[226:227] op_sel:[0,1,0]
	v_pk_fma_f32 v[228:229], v[208:209], v[96:97], v[228:229] op_sel:[0,1,0]
	v_pk_fma_f32 v[226:227], v[210:211], v[108:109], v[226:227] op_sel_hi:[1,0,1]
	v_pk_fma_f32 v[228:229], v[210:211], v[98:99], v[228:229] op_sel_hi:[1,0,1]
	v_pk_fma_f32 v[226:227], v[212:213], v[108:109], v[226:227] op_sel:[0,1,0]
	v_pk_fma_f32 v[228:229], v[212:213], v[98:99], v[228:229] op_sel:[0,1,0]
	v_pk_mul_f32 v[232:233], v[118:119], v[114:115] op_sel_hi:[1,0]
	v_add_f32_dpp v230, v227, v226 row_ror:8 row_mask:0xf bank_mask:0xf
	v_pk_mul_f32 v[234:235], v[118:119], v[114:115] op_sel:[0,1]
	v_pk_mul_f32 v[236:237], v[118:119], v[116:117] op_sel_hi:[1,0]
	v_add_f32_dpp v230, v230, v230 quad_perm:[1,0,3,2] row_mask:0xf bank_mask:0xf
	v_pk_mul_f32 v[238:239], v[118:119], v[116:117] op_sel:[0,1]
	ds_read_b128 v[96:99], v241 offset:2048
	v_add_f32_dpp v230, v230, v230 quad_perm:[2,3,0,1] row_mask:0xf bank_mask:0xf
	v_pk_fma_f32 v[232:233], v[206:207], v[102:103], v[232:233] op_sel_hi:[1,0,1]
	v_pk_fma_f32 v[234:235], v[208:209], v[102:103], v[234:235] op_sel:[0,1,0]
	v_add_f32_dpp v230, v230, v230 row_half_mirror row_mask:0xf bank_mask:0xf
	v_pk_fma_f32 v[236:237], v[210:211], v[104:105], v[236:237] op_sel_hi:[1,0,1]
	v_pk_fma_f32 v[238:239], v[212:213], v[104:105], v[238:239] op_sel:[0,1,0]
	v_mov_b32_dpp v231, v230 row_ror:8 row_mask:0xf bank_mask:0xf
	ds_write_b64 v217, v[228:229] offset:3456
	v_pk_fma_f32 v[206:207], v[110:111], v[230:231], v[232:233] op_sel_hi:[0,1,1] neg_lo:[1,0,0] neg_hi:[1,0,0]
	v_pk_fma_f32 v[208:209], v[110:111], v[230:231], v[234:235] op_sel:[1,0,0] neg_lo:[1,0,0] neg_hi:[1,0,0]
	v_pk_fma_f32 v[210:211], v[112:113], v[230:231], v[236:237] op_sel_hi:[0,1,1] neg_lo:[1,0,0] neg_hi:[1,0,0]
	v_pk_fma_f32 v[212:213], v[112:113], v[230:231], v[238:239] op_sel:[1,0,0] neg_lo:[1,0,0] neg_hi:[1,0,0]
	ds_read_b128 v[106:109], v240 offset:18688
	ds_read_b64 v[118:119], v242 offset:2304
	ds_read_b128 v[114:117], v240 offset:51456
	ds_read_b128 v[102:105], v240 offset:2304
	ds_read_b128 v[110:113], v240 offset:35072
	s_waitcnt lgkmcnt(7)
	v_pk_mul_f32 v[226:227], v[206:207], v[84:85] op_sel_hi:[1,0]
	v_pk_mul_f32 v[228:229], v[206:207], v[222:223] op_sel_hi:[1,0]
	v_pk_fma_f32 v[226:227], v[208:209], v[84:85], v[226:227] op_sel:[0,1,0]
	v_pk_fma_f32 v[228:229], v[208:209], v[222:223], v[228:229] op_sel:[0,1,0]
	v_pk_fma_f32 v[226:227], v[210:211], v[86:87], v[226:227] op_sel_hi:[1,0,1]
	v_pk_fma_f32 v[228:229], v[210:211], v[224:225], v[228:229] op_sel_hi:[1,0,1]
	v_pk_fma_f32 v[226:227], v[212:213], v[86:87], v[226:227] op_sel:[0,1,0]
	v_pk_fma_f32 v[228:229], v[212:213], v[224:225], v[228:229] op_sel:[0,1,0]
	v_pk_mul_f32 v[232:233], v[100:101], v[92:93] op_sel_hi:[1,0]
	v_add_f32_dpp v230, v227, v226 row_ror:8 row_mask:0xf bank_mask:0xf
	v_pk_mul_f32 v[234:235], v[100:101], v[92:93] op_sel:[0,1]
	v_pk_mul_f32 v[236:237], v[100:101], v[94:95] op_sel_hi:[1,0]
	v_add_f32_dpp v230, v230, v230 quad_perm:[1,0,3,2] row_mask:0xf bank_mask:0xf
	v_pk_mul_f32 v[238:239], v[100:101], v[94:95] op_sel:[0,1]
	ds_read_b128 v[222:225], v241 offset:2304
	v_add_f32_dpp v230, v230, v230 quad_perm:[2,3,0,1] row_mask:0xf bank_mask:0xf
	v_pk_fma_f32 v[232:233], v[206:207], v[80:81], v[232:233] op_sel_hi:[1,0,1]
	v_pk_fma_f32 v[234:235], v[208:209], v[80:81], v[234:235] op_sel:[0,1,0]
	v_add_f32_dpp v230, v230, v230 row_half_mirror row_mask:0xf bank_mask:0xf
	v_pk_fma_f32 v[236:237], v[210:211], v[82:83], v[236:237] op_sel_hi:[1,0,1]
	v_pk_fma_f32 v[238:239], v[212:213], v[82:83], v[238:239] op_sel:[0,1,0]
	v_mov_b32_dpp v231, v230 row_ror:8 row_mask:0xf bank_mask:0xf
	ds_write_b64 v217, v[228:229] offset:4032
	v_pk_fma_f32 v[206:207], v[88:89], v[230:231], v[232:233] op_sel_hi:[0,1,1] neg_lo:[1,0,0] neg_hi:[1,0,0]
	v_pk_fma_f32 v[208:209], v[88:89], v[230:231], v[234:235] op_sel:[1,0,0] neg_lo:[1,0,0] neg_hi:[1,0,0]
	v_pk_fma_f32 v[210:211], v[90:91], v[230:231], v[236:237] op_sel_hi:[0,1,1] neg_lo:[1,0,0] neg_hi:[1,0,0]
	v_pk_fma_f32 v[212:213], v[90:91], v[230:231], v[238:239] op_sel:[1,0,0] neg_lo:[1,0,0] neg_hi:[1,0,0]
	ds_read_b128 v[84:87], v240 offset:18944
	ds_read_b64 v[100:101], v242 offset:2560
	ds_read_b128 v[92:95], v240 offset:51712
	ds_read_b128 v[80:83], v240 offset:2560
	ds_read_b128 v[88:91], v240 offset:35328
	s_waitcnt lgkmcnt(7)
; template <int CTRL> __device__ __forceinline__ float dppf(float x) { return __builtin_bit_cast(float, __builtin_amdgcn_update_dpp(0, __builtin_bit_cast(int, x), CTRL, 0xF, 0xF, false)); }
; __device__ __forceinline__ void phase_rwkv_scan(const Fr& F, int jr) {
;     ...
;                 for (int pg = 0; pg < 64; pg += 16) {
; #pragma unroll
;                     for (int pi = 0; pi < 16; ++pi) {
;                         const int p = pg + pi, pn = p < 63 ? p + 1 : 63;
;                         const f32x4 w4n = PW[pn * 16], k4n = PW[1024 + pn * 16], b4n = PW[2048 + pn * 16], d4n = PW[3072 + pn * 16], r4n = PR[pn * 16];
;                         const float vvn = PV[pn * 32];
;                         f32x2 t = S01 * k4.xy; t = S23 * k4.zw + t; float sa = t.x + t.y;
;                         sa += dppf<0x128>(sa);
;                         const f32x2 dv01 = d4.xy * vv, dv23 = d4.zw * vv;
;                         sa += dppf<0x124>(sa);
;                         const f32x2 e01 = S01 * w4.xy + dv01;
;                         sa += dppf<0x122>(sa);
;                         const f32x2 e23 = S23 * w4.zw + dv23;
;                         sa += dppf<0x121>(sa);
;                         S01 = e01 - b4.xy * sa; S23 = e23 - b4.zw * sa;
;                         f32x2 u = S01 * r4.xy; u = S23 * r4.zw + u;
;                         PY[pi * 64] = u.x + u.y;
;                         w4 = w4n; k4 = k4n; b4 = b4n; d4 = d4n; r4 = r4n; vv = vvn;
;                     }
	v_pk_mul_f32 v[226:227], v[206:207], v[106:107] op_sel_hi:[1,0]
	v_pk_mul_f32 v[228:229], v[206:207], v[96:97] op_sel_hi:[1,0]
	v_pk_fma_f32 v[226:227], v[208:209], v[106:107], v[226:227] op_sel:[0,1,0]
	v_pk_fma_f32 v[228:229], v[208:209], v[96:97], v[228:229] op_sel:[0,1,0]
	v_pk_fma_f32 v[226:227], v[210:211], v[108:109], v[226:227] op_sel_hi:[1,0,1]
	v_pk_fma_f32 v[228:229], v[210:211], v[98:99], v[228:229] op_sel_hi:[1,0,1]
	v_pk_fma_f32 v[226:227], v[212:213], v[108:109], v[226:227] op_sel:[0,1,0]
	v_pk_fma_f32 v[228:229], v[212:213], v[98:99], v[228:229] op_sel:[0,1,0]
	v_pk_mul_f32 v[232:233], v[118:119], v[114:115] op_sel_hi:[1,0]
	v_add_f32_dpp v230, v227, v226 row_ror:8 row_mask:0xf bank_mask:0xf
	v_pk_mul_f32 v[234:235], v[118:119], v[114:115] op_sel:[0,1]
	v_pk_mul_f32 v[236:237], v[118:119], v[116:117] op_sel_hi:[1,0]
	v_add_f32_dpp v230, v230, v230 quad_perm:[1,0,3,2] row_mask:0xf bank_mask:0xf
	v_pk_mul_f32 v[238:239], v[118:119], v[116:117] op_sel:[0,1]
	ds_read_b128 v[96:99], v241 offset:2560
	v_add_f32_dpp v230, v230, v230 quad_perm:[2,3,0,1] row_mask:0xf bank_mask:0xf
	v_pk_fma_f32 v[232:233], v[206:207], v[102:103], v[232:233] op_sel_hi:[1,0,1]
	v_pk_fma_f32 v[234:235], v[208:209], v[102:103], v[234:235] op_sel:[0,1,0]
	v_add_f32_dpp v230, v230, v230 row_half_mirror row_mask:0xf bank_mask:0xf
	v_pk_fma_f32 v[236:237], v[210:211], v[104:105], v[236:237] op_sel_hi:[1,0,1]
	v_pk_fma_f32 v[238:239], v[212:213], v[104:105], v[238:239] op_sel:[0,1,0]
	v_mov_b32_dpp v231, v230 row_ror:8 row_mask:0xf bank_mask:0xf
	ds_write_b64 v217, v[228:229] offset:4608
	v_pk_fma_f32 v[206:207], v[110:111], v[230:231], v[232:233] op_sel_hi:[0,1,1] neg_lo:[1,0,0] neg_hi:[1,0,0]
	v_pk_fma_f32 v[208:209], v[110:111], v[230:231], v[234:235] op_sel:[1,0,0] neg_lo:[1,0,0] neg_hi:[1,0,0]
	v_pk_fma_f32 v[210:211], v[112:113], v[230:231], v[236:237] op_sel_hi:[0,1,1] neg_lo:[1,0,0] neg_hi:[1,0,0]
	v_pk_fma_f32 v[212:213], v[112:113], v[230:231], v[238:239] op_sel:[1,0,0] neg_lo:[1,0,0] neg_hi:[1,0,0]
	ds_read_b128 v[106:109], v240 offset:19200
	ds_read_b64 v[118:119], v242 offset:2816
	ds_read_b128 v[114:117], v240 offset:51968
	ds_read_b128 v[102:105], v240 offset:2816
	ds_read_b128 v[110:113], v240 offset:35584
	s_waitcnt lgkmcnt(7)
	v_pk_mul_f32 v[226:227], v[206:207], v[84:85] op_sel_hi:[1,0]
	v_pk_mul_f32 v[228:229], v[206:207], v[222:223] op_sel_hi:[1,0]
	v_pk_fma_f32 v[226:227], v[208:209], v[84:85], v[226:227] op_sel:[0,1,0]
	v_pk_fma_f32 v[228:229], v[208:209], v[222:223], v[228:229] op_sel:[0,1,0]
	v_pk_fma_f32 v[226:227], v[210:211], v[86:87], v[226:227] op_sel_hi:[1,0,1]
	v_pk_fma_f32 v[228:229], v[210:211], v[224:225], v[228:229] op_sel_hi:[1,0,1]
	v_pk_fma_f32 v[226:227], v[212:213], v[86:87], v[226:227] op_sel:[0,1,0]
	v_pk_fma_f32 v[228:229], v[212:213], v[224:225], v[228:229] op_sel:[0,1,0]
	v_pk_mul_f32 v[232:233], v[100:101], v[92:93] op_sel_hi:[1,0]
	v_add_f32_dpp v230, v227, v226 row_ror:8 row_mask:0xf bank_mask:0xf
	v_pk_mul_f32 v[234:235], v[100:101], v[92:93] op_sel:[0,1]
	v_pk_mul_f32 v[236:237], v[100:101], v[94:95] op_sel_hi:[1,0]
	v_add_f32_dpp v230, v230, v230 quad_perm:[1,0,3,2] row_mask:0xf bank_mask:0xf
	v_pk_mul_f32 v[238:239], v[100:101], v[94:95] op_sel:[0,1]
	ds_read_b128 v[222:225], v241 offset:2816
	v_add_f32_dpp v230, v230, v230 quad_perm:[2,3,0,1] row_mask:0xf bank_mask:0xf
	v_pk_fma_f32 v[232:233], v[206:207], v[80:81], v[232:233] op_sel_hi:[1,0,1]
	v_pk_fma_f32 v[234:235], v[208:209], v[80:81], v[234:235] op_sel:[0,1,0]
	v_add_f32_dpp v230, v230, v230 row_half_mirror row_mask:0xf bank_mask:0xf
	v_pk_fma_f32 v[236:237], v[210:211], v[82:83], v[236:237] op_sel_hi:[1,0,1]
	v_pk_fma_f32 v[238:239], v[212:213], v[82:83], v[238:239] op_sel:[0,1,0]
	v_mov_b32_dpp v231, v230 row_ror:8 row_mask:0xf bank_mask:0xf
	ds_write_b64 v217, v[228:229] offset:5184
	v_pk_fma_f32 v[206:207], v[88:89], v[230:231], v[232:233] op_sel_hi:[0,1,1] neg_lo:[1,0,0] neg_hi:[1,0,0]
	v_pk_fma_f32 v[208:209], v[88:89], v[230:231], v[234:235] op_sel:[1,0,0] neg_lo:[1,0,0] neg_hi:[1,0,0]
	v_pk_fma_f32 v[210:211], v[90:91], v[230:231], v[236:237] op_sel_hi:[0,1,1] neg_lo:[1,0,0] neg_hi:[1,0,0]
	v_pk_fma_f32 v[212:213], v[90:91], v[230:231], v[238:239] op_sel:[1,0,0] neg_lo:[1,0,0] neg_hi:[1,0,0]
	ds_read_b128 v[84:87], v240 offset:19456
	ds_read_b64 v[100:101], v242 offset:3072
	ds_read_b128 v[92:95], v240 offset:52224
	ds_read_b128 v[80:83], v240 offset:3072
	ds_read_b128 v[88:91], v240 offset:35840
	s_waitcnt lgkmcnt(7)
	v_pk_mul_f32 v[226:227], v[206:207], v[106:107] op_sel_hi:[1,0]
	v_pk_mul_f32 v[228:229], v[206:207], v[96:97] op_sel_hi:[1,0]
	v_pk_fma_f32 v[226:227], v[208:209], v[106:107], v[226:227] op_sel:[0,1,0]
	v_pk_fma_f32 v[228:229], v[208:209], v[96:97], v[228:229] op_sel:[0,1,0]
	v_pk_fma_f32 v[226:227], v[210:211], v[108:109], v[226:227] op_sel_hi:[1,0,1]
	v_pk_fma_f32 v[228:229], v[210:211], v[98:99], v[228:229] op_sel_hi:[1,0,1]
	v_pk_fma_f32 v[226:227], v[212:213], v[108:109], v[226:227] op_sel:[0,1,0]
	v_pk_fma_f32 v[228:229], v[212:213], v[98:99], v[228:229] op_sel:[0,1,0]
	v_pk_mul_f32 v[232:233], v[118:119], v[114:115] op_sel_hi:[1,0]
	v_add_f32_dpp v230, v227, v226 row_ror:8 row_mask:0xf bank_mask:0xf
	v_pk_mul_f32 v[234:235], v[118:119], v[114:115] op_sel:[0,1]
	v_pk_mul_f32 v[236:237], v[118:119], v[116:117] op_sel_hi:[1,0]
	v_add_f32_dpp v230, v230, v230 quad_perm:[1,0,3,2] row_mask:0xf bank_mask:0xf
	v_pk_mul_f32 v[238:239], v[118:119], v[116:117] op_sel:[0,1]
	ds_read_b128 v[96:99], v241 offset:3072
	v_add_f32_dpp v230, v230, v230 quad_perm:[2,3,0,1] row_mask:0xf bank_mask:0xf
	v_pk_fma_f32 v[232:233], v[206:207], v[102:103], v[232:233] op_sel_hi:[1,0,1]
	v_pk_fma_f32 v[234:235], v[208:209], v[102:103], v[234:235] op_sel:[0,1,0]
	v_add_f32_dpp v230, v230, v230 row_half_mirror row_mask:0xf bank_mask:0xf
	v_pk_fma_f32 v[236:237], v[210:211], v[104:105], v[236:237] op_sel_hi:[1,0,1]
	v_pk_fma_f32 v[238:239], v[212:213], v[104:105], v[238:239] op_sel:[0,1,0]
	v_mov_b32_dpp v231, v230 row_ror:8 row_mask:0xf bank_mask:0xf
	ds_write_b64 v217, v[228:229] offset:5760
	v_pk_fma_f32 v[206:207], v[110:111], v[230:231], v[232:233] op_sel_hi:[0,1,1] neg_lo:[1,0,0] neg_hi:[1,0,0]
	v_pk_fma_f32 v[208:209], v[110:111], v[230:231], v[234:235] op_sel:[1,0,0] neg_lo:[1,0,0] neg_hi:[1,0,0]
	v_pk_fma_f32 v[210:211], v[112:113], v[230:231], v[236:237] op_sel_hi:[0,1,1] neg_lo:[1,0,0] neg_hi:[1,0,0]
	v_pk_fma_f32 v[212:213], v[112:113], v[230:231], v[238:239] op_sel:[1,0,0] neg_lo:[1,0,0] neg_hi:[1,0,0]
	ds_read_b128 v[106:109], v240 offset:19712
	ds_read_b64 v[118:119], v242 offset:3328
	ds_read_b128 v[114:117], v240 offset:52480
	ds_read_b128 v[102:105], v240 offset:3328
	ds_read_b128 v[110:113], v240 offset:36096
	s_waitcnt lgkmcnt(7)
; template <int CTRL> __device__ __forceinline__ float dppf(float x) { return __builtin_bit_cast(float, __builtin_amdgcn_update_dpp(0, __builtin_bit_cast(int, x), CTRL, 0xF, 0xF, false)); }
; __device__ __forceinline__ void phase_rwkv_scan(const Fr& F, int jr) {
;     ...
;                 for (int pg = 0; pg < 64; pg += 16) {
; #pragma unroll
;                     for (int pi = 0; pi < 16; ++pi) {
;                         const int p = pg + pi, pn = p < 63 ? p + 1 : 63;
;                         const f32x4 w4n = PW[pn * 16], k4n = PW[1024 + pn * 16], b4n = PW[2048 + pn * 16], d4n = PW[3072 + pn * 16], r4n = PR[pn * 16];
;                         const float vvn = PV[pn * 32];
;                         f32x2 t = S01 * k4.xy; t = S23 * k4.zw + t; float sa = t.x + t.y;
;                         sa += dppf<0x128>(sa);
;                         const f32x2 dv01 = d4.xy * vv, dv23 = d4.zw * vv;
;                         sa += dppf<0x124>(sa);
;                         const f32x2 e01 = S01 * w4.xy + dv01;
;                         sa += dppf<0x122>(sa);
;                         const f32x2 e23 = S23 * w4.zw + dv23;
;                         sa += dppf<0x121>(sa);
;                         S01 = e01 - b4.xy * sa; S23 = e23 - b4.zw * sa;
;                         f32x2 u = S01 * r4.xy; u = S23 * r4.zw + u;
;                         PY[pi * 64] = u.x + u.y;
;                         w4 = w4n; k4 = k4n; b4 = b4n; d4 = d4n; r4 = r4n; vv = vvn;
;                     }
	v_pk_mul_f32 v[226:227], v[206:207], v[84:85] op_sel_hi:[1,0]
	v_pk_mul_f32 v[228:229], v[206:207], v[222:223] op_sel_hi:[1,0]
	v_pk_fma_f32 v[226:227], v[208:209], v[84:85], v[226:227] op_sel:[0,1,0]
	v_pk_fma_f32 v[228:229], v[208:209], v[222:223], v[228:229] op_sel:[0,1,0]
	v_pk_fma_f32 v[226:227], v[210:211], v[86:87], v[226:227] op_sel_hi:[1,0,1]
	v_pk_fma_f32 v[228:229], v[210:211], v[224:225], v[228:229] op_sel_hi:[1,0,1]
	v_pk_fma_f32 v[226:227], v[212:213], v[86:87], v[226:227] op_sel:[0,1,0]
	v_pk_fma_f32 v[228:229], v[212:213], v[224:225], v[228:229] op_sel:[0,1,0]
	v_pk_mul_f32 v[232:233], v[100:101], v[92:93] op_sel_hi:[1,0]
	v_add_f32_dpp v230, v227, v226 row_ror:8 row_mask:0xf bank_mask:0xf
	v_pk_mul_f32 v[234:235], v[100:101], v[92:93] op_sel:[0,1]
	v_pk_mul_f32 v[236:237], v[100:101], v[94:95] op_sel_hi:[1,0]
	v_add_f32_dpp v230, v230, v230 quad_perm:[1,0,3,2] row_mask:0xf bank_mask:0xf
	v_pk_mul_f32 v[238:239], v[100:101], v[94:95] op_sel:[0,1]
	ds_read_b128 v[222:225], v241 offset:3328
	v_add_f32_dpp v230, v230, v230 quad_perm:[2,3,0,1] row_mask:0xf bank_mask:0xf
	v_pk_fma_f32 v[232:233], v[206:207], v[80:81], v[232:233] op_sel_hi:[1,0,1]
	v_pk_fma_f32 v[234:235], v[208:209], v[80:81], v[234:235] op_sel:[0,1,0]
	v_add_f32_dpp v230, v230, v230 row_half_mirror row_mask:0xf bank_mask:0xf
	v_pk_fma_f32 v[236:237], v[210:211], v[82:83], v[236:237] op_sel_hi:[1,0,1]
	v_pk_fma_f32 v[238:239], v[212:213], v[82:83], v[238:239] op_sel:[0,1,0]
	v_mov_b32_dpp v231, v230 row_ror:8 row_mask:0xf bank_mask:0xf
	ds_write_b64 v217, v[228:229] offset:6336
	v_pk_fma_f32 v[206:207], v[88:89], v[230:231], v[232:233] op_sel_hi:[0,1,1] neg_lo:[1,0,0] neg_hi:[1,0,0]
	v_pk_fma_f32 v[208:209], v[88:89], v[230:231], v[234:235] op_sel:[1,0,0] neg_lo:[1,0,0] neg_hi:[1,0,0]
	v_pk_fma_f32 v[210:211], v[90:91], v[230:231], v[236:237] op_sel_hi:[0,1,1] neg_lo:[1,0,0] neg_hi:[1,0,0]
	v_pk_fma_f32 v[212:213], v[90:91], v[230:231], v[238:239] op_sel:[1,0,0] neg_lo:[1,0,0] neg_hi:[1,0,0]
	ds_read_b128 v[84:87], v240 offset:19968
	ds_read_b64 v[100:101], v242 offset:3584
	ds_read_b128 v[92:95], v240 offset:52736
	ds_read_b128 v[80:83], v240 offset:3584
	ds_read_b128 v[88:91], v240 offset:36352
	s_waitcnt lgkmcnt(7)
	v_pk_mul_f32 v[226:227], v[206:207], v[106:107] op_sel_hi:[1,0]
	v_pk_mul_f32 v[228:229], v[206:207], v[96:97] op_sel_hi:[1,0]
	v_pk_fma_f32 v[226:227], v[208:209], v[106:107], v[226:227] op_sel:[0,1,0]
	v_pk_fma_f32 v[228:229], v[208:209], v[96:97], v[228:229] op_sel:[0,1,0]
	v_pk_fma_f32 v[226:227], v[210:211], v[108:109], v[226:227] op_sel_hi:[1,0,1]
	v_pk_fma_f32 v[228:229], v[210:211], v[98:99], v[228:229] op_sel_hi:[1,0,1]
	v_pk_fma_f32 v[226:227], v[212:213], v[108:109], v[226:227] op_sel:[0,1,0]
	v_pk_fma_f32 v[228:229], v[212:213], v[98:99], v[228:229] op_sel:[0,1,0]
	v_pk_mul_f32 v[232:233], v[118:119], v[114:115] op_sel_hi:[1,0]
	v_add_f32_dpp v230, v227, v226 row_ror:8 row_mask:0xf bank_mask:0xf
	v_pk_mul_f32 v[234:235], v[118:119], v[114:115] op_sel:[0,1]
	v_pk_mul_f32 v[236:237], v[118:119], v[116:117] op_sel_hi:[1,0]
	v_add_f32_dpp v230, v230, v230 quad_perm:[1,0,3,2] row_mask:0xf bank_mask:0xf
	v_pk_mul_f32 v[238:239], v[118:119], v[116:117] op_sel:[0,1]
	ds_read_b128 v[96:99], v241 offset:3584
	v_add_f32_dpp v230, v230, v230 quad_perm:[2,3,0,1] row_mask:0xf bank_mask:0xf
	v_pk_fma_f32 v[232:233], v[206:207], v[102:103], v[232:233] op_sel_hi:[1,0,1]
	v_pk_fma_f32 v[234:235], v[208:209], v[102:103], v[234:235] op_sel:[0,1,0]
	v_add_f32_dpp v230, v230, v230 row_half_mirror row_mask:0xf bank_mask:0xf
	v_pk_fma_f32 v[236:237], v[210:211], v[104:105], v[236:237] op_sel_hi:[1,0,1]
	v_pk_fma_f32 v[238:239], v[212:213], v[104:105], v[238:239] op_sel:[0,1,0]
	v_mov_b32_dpp v231, v230 row_ror:8 row_mask:0xf bank_mask:0xf
	ds_write_b64 v217, v[228:229] offset:6912
	v_pk_fma_f32 v[206:207], v[110:111], v[230:231], v[232:233] op_sel_hi:[0,1,1] neg_lo:[1,0,0] neg_hi:[1,0,0]
	v_pk_fma_f32 v[208:209], v[110:111], v[230:231], v[234:235] op_sel:[1,0,0] neg_lo:[1,0,0] neg_hi:[1,0,0]
	v_pk_fma_f32 v[210:211], v[112:113], v[230:231], v[236:237] op_sel_hi:[0,1,1] neg_lo:[1,0,0] neg_hi:[1,0,0]
	v_pk_fma_f32 v[212:213], v[112:113], v[230:231], v[238:239] op_sel:[1,0,0] neg_lo:[1,0,0] neg_hi:[1,0,0]
	ds_read_b128 v[106:109], v240 offset:20224
	ds_read_b64 v[118:119], v242 offset:3840
	ds_read_b128 v[114:117], v240 offset:52992
	ds_read_b128 v[102:105], v240 offset:3840
	ds_read_b128 v[110:113], v240 offset:36608
	s_waitcnt lgkmcnt(7)
; __device__ __forceinline__ unsigned f2bf(float f) { unsigned u = __builtin_bit_cast(unsigned, f); return (u + 0x7fffu + ((u >> 16) & 1u)) >> 16; }
; __device__ __forceinline__ void phase_rwkv_scan(const Fr& F, int jr) {
;     ...
;                 for (int pg = 0; pg < 64; pg += 16) {
; #pragma unroll
;                     for (int pi = 0; pi < 16; ++pi) {
;                         const int p = pg + pi, pn = p < 63 ? p + 1 : 63;
;                         const f32x4 w4n = PW[pn * 16], k4n = PW[1024 + pn * 16], b4n = PW[2048 + pn * 16], d4n = PW[3072 + pn * 16], r4n = PR[pn * 16];
;                         const float vvn = PV[pn * 32];
;                         f32x2 t = S01 * k4.xy; t = S23 * k4.zw + t; float sa = t.x + t.y;
;                         sa += dppf<0x128>(sa);
;                         const f32x2 dv01 = d4.xy * vv, dv23 = d4.zw * vv;
;                         sa += dppf<0x124>(sa);
;                         const f32x2 e01 = S01 * w4.xy + dv01;
;                         sa += dppf<0x122>(sa);
;                         const f32x2 e23 = S23 * w4.zw + dv23;
;                         sa += dppf<0x121>(sa);
;                         S01 = e01 - b4.xy * sa; S23 = e23 - b4.zw * sa;
;                         f32x2 u = S01 * r4.xy; u = S23 * r4.zw + u;
;                         PY[pi * 64] = u.x + u.y;
;                         w4 = w4n; k4 = k4n; b4 = b4n; d4 = d4n; r4 = r4n; vv = vvn;
;                     }
;                     asm volatile("s_waitcnt lgkmcnt(0)" ::: "memory");
;                     {
;                         const int j = lane >> 2, q = lane & 3; const float* yp = Ypw + j * 64 + q * 16;
;                         const f32x4 a0 = *(const f32x4*)yp, a1 = *(const f32x4*)(yp + 4), a2 = *(const f32x4*)(yp + 8), a3 = *(const f32x4*)(yp + 12);
;                         const f32x4 ssum = (a0 + a1) + (a2 + a3); const float yv = (ssum.x + ssum.y) + (ssum.z + ssum.w);
;                         const size_t row = (size_t)b * TB + tokof(s, chunk * 64 + pg + j);
;                         Yb[row * D + h * 64 + 32 * half + 4 * wave + q] = (bf16)f2bf(yv);
;                     }
;                     asm volatile("s_waitcnt lgkmcnt(0)" ::: "memory");
;                 }
	v_pk_mul_f32 v[226:227], v[206:207], v[84:85] op_sel_hi:[1,0]
	v_pk_mul_f32 v[228:229], v[206:207], v[222:223] op_sel_hi:[1,0]
	v_pk_fma_f32 v[226:227], v[208:209], v[84:85], v[226:227] op_sel:[0,1,0]
	v_pk_fma_f32 v[228:229], v[208:209], v[222:223], v[228:229] op_sel:[0,1,0]
	v_pk_fma_f32 v[226:227], v[210:211], v[86:87], v[226:227] op_sel_hi:[1,0,1]
	v_pk_fma_f32 v[228:229], v[210:211], v[224:225], v[228:229] op_sel_hi:[1,0,1]
	v_pk_fma_f32 v[226:227], v[212:213], v[86:87], v[226:227] op_sel:[0,1,0]
	v_pk_fma_f32 v[228:229], v[212:213], v[224:225], v[228:229] op_sel:[0,1,0]
	v_pk_mul_f32 v[232:233], v[100:101], v[92:93] op_sel_hi:[1,0]
	v_add_f32_dpp v230, v227, v226 row_ror:8 row_mask:0xf bank_mask:0xf
	v_pk_mul_f32 v[234:235], v[100:101], v[92:93] op_sel:[0,1]
	v_pk_mul_f32 v[236:237], v[100:101], v[94:95] op_sel_hi:[1,0]
	v_add_f32_dpp v230, v230, v230 quad_perm:[1,0,3,2] row_mask:0xf bank_mask:0xf
	v_pk_mul_f32 v[238:239], v[100:101], v[94:95] op_sel:[0,1]
	ds_read_b128 v[222:225], v241 offset:3840
	v_add_f32_dpp v230, v230, v230 quad_perm:[2,3,0,1] row_mask:0xf bank_mask:0xf
	v_pk_fma_f32 v[232:233], v[206:207], v[80:81], v[232:233] op_sel_hi:[1,0,1]
	v_pk_fma_f32 v[234:235], v[208:209], v[80:81], v[234:235] op_sel:[0,1,0]
	v_add_f32_dpp v230, v230, v230 row_half_mirror row_mask:0xf bank_mask:0xf
	v_pk_fma_f32 v[236:237], v[210:211], v[82:83], v[236:237] op_sel_hi:[1,0,1]
	v_pk_fma_f32 v[238:239], v[212:213], v[82:83], v[238:239] op_sel:[0,1,0]
	v_mov_b32_dpp v231, v230 row_ror:8 row_mask:0xf bank_mask:0xf
	ds_write_b64 v217, v[228:229] offset:7488
	v_pk_fma_f32 v[206:207], v[88:89], v[230:231], v[232:233] op_sel_hi:[0,1,1] neg_lo:[1,0,0] neg_hi:[1,0,0]
	v_pk_fma_f32 v[208:209], v[88:89], v[230:231], v[234:235] op_sel:[1,0,0] neg_lo:[1,0,0] neg_hi:[1,0,0]
	v_pk_fma_f32 v[210:211], v[90:91], v[230:231], v[236:237] op_sel_hi:[0,1,1] neg_lo:[1,0,0] neg_hi:[1,0,0]
	v_pk_fma_f32 v[212:213], v[90:91], v[230:231], v[238:239] op_sel:[1,0,0] neg_lo:[1,0,0] neg_hi:[1,0,0]
	ds_read_b128 v[84:87], v240 offset:20480
	ds_read_b64 v[100:101], v242 offset:4096
	ds_read_b128 v[92:95], v240 offset:53248
	ds_read_b128 v[80:83], v240 offset:4096
	ds_read_b128 v[88:91], v240 offset:36864
	s_waitcnt lgkmcnt(7)
	v_pk_mul_f32 v[226:227], v[206:207], v[106:107] op_sel_hi:[1,0]
	v_pk_mul_f32 v[228:229], v[206:207], v[96:97] op_sel_hi:[1,0]
	v_pk_fma_f32 v[226:227], v[208:209], v[106:107], v[226:227] op_sel:[0,1,0]
	v_pk_fma_f32 v[228:229], v[208:209], v[96:97], v[228:229] op_sel:[0,1,0]
	v_pk_fma_f32 v[226:227], v[210:211], v[108:109], v[226:227] op_sel_hi:[1,0,1]
	v_pk_fma_f32 v[228:229], v[210:211], v[98:99], v[228:229] op_sel_hi:[1,0,1]
	v_pk_fma_f32 v[226:227], v[212:213], v[108:109], v[226:227] op_sel:[0,1,0]
	v_pk_fma_f32 v[228:229], v[212:213], v[98:99], v[228:229] op_sel:[0,1,0]
	v_pk_mul_f32 v[232:233], v[118:119], v[114:115] op_sel_hi:[1,0]
	v_add_f32_dpp v230, v227, v226 row_ror:8 row_mask:0xf bank_mask:0xf
	v_pk_mul_f32 v[234:235], v[118:119], v[114:115] op_sel:[0,1]
	v_pk_mul_f32 v[236:237], v[118:119], v[116:117] op_sel_hi:[1,0]
	v_add_f32_dpp v230, v230, v230 quad_perm:[1,0,3,2] row_mask:0xf bank_mask:0xf
	v_pk_mul_f32 v[238:239], v[118:119], v[116:117] op_sel:[0,1]
	ds_read_b128 v[96:99], v241 offset:4096
	v_add_f32_dpp v230, v230, v230 quad_perm:[2,3,0,1] row_mask:0xf bank_mask:0xf
	v_pk_fma_f32 v[232:233], v[206:207], v[102:103], v[232:233] op_sel_hi:[1,0,1]
	v_pk_fma_f32 v[234:235], v[208:209], v[102:103], v[234:235] op_sel:[0,1,0]
	v_add_f32_dpp v230, v230, v230 row_half_mirror row_mask:0xf bank_mask:0xf
	v_pk_fma_f32 v[236:237], v[210:211], v[104:105], v[236:237] op_sel_hi:[1,0,1]
	v_pk_fma_f32 v[238:239], v[212:213], v[104:105], v[238:239] op_sel:[0,1,0]
	v_mov_b32_dpp v231, v230 row_ror:8 row_mask:0xf bank_mask:0xf
	ds_write_b64 v217, v[228:229] offset:8064
	v_pk_fma_f32 v[206:207], v[110:111], v[230:231], v[232:233] op_sel_hi:[0,1,1] neg_lo:[1,0,0] neg_hi:[1,0,0]
	v_pk_fma_f32 v[208:209], v[110:111], v[230:231], v[234:235] op_sel:[1,0,0] neg_lo:[1,0,0] neg_hi:[1,0,0]
	v_pk_fma_f32 v[210:211], v[112:113], v[230:231], v[236:237] op_sel_hi:[0,1,1] neg_lo:[1,0,0] neg_hi:[1,0,0]
	v_pk_fma_f32 v[212:213], v[112:113], v[230:231], v[238:239] op_sel:[1,0,0] neg_lo:[1,0,0] neg_hi:[1,0,0]
	s_waitcnt lgkmcnt(8)
	v_pk_mul_f32 v[228:229], v[206:207], v[222:223] op_sel_hi:[1,0]
	v_add_u32_e32 v243, s90, v219
	v_pk_fma_f32 v[228:229], v[208:209], v[222:223], v[228:229] op_sel:[0,1,0]
	v_lshl_add_u32 v243, v243, 11, v220
	v_pk_fma_f32 v[228:229], v[210:211], v[224:225], v[228:229] op_sel_hi:[1,0,1]
	v_add_u32_e32 v240, 0x1000, v240
	v_pk_fma_f32 v[228:229], v[212:213], v[224:225], v[228:229] op_sel:[0,1,0]
	v_add_u32_e32 v241, 0x1000, v241
	v_add_u32_e32 v242, 0x1000, v242
	s_waitcnt lgkmcnt(1)
	ds_write_b64 v217, v[228:229] offset:8640
	ds_read_b128 v[102:105], v218 offset:0
	ds_read_b128 v[106:109], v218 offset:16
	ds_read_b128 v[110:113], v218 offset:32
	ds_read_b128 v[114:117], v218 offset:48
	ds_read_b128 v[222:225], v218 offset:64
	ds_read_b128 v[232:235], v218 offset:80
	ds_read_b128 v[236:239], v218 offset:96
	ds_read_b128 v[226:229], v218 offset:112
	s_waitcnt lgkmcnt(6)
	v_pk_add_f32 v[102:103], v[102:103], v[104:105]
	v_pk_add_f32 v[106:107], v[106:107], v[108:109]
	s_waitcnt lgkmcnt(4)
	v_pk_add_f32 v[110:111], v[110:111], v[112:113]
	v_pk_add_f32 v[114:115], v[114:115], v[116:117]
	v_pk_add_f32 v[102:103], v[102:103], v[106:107]
	s_waitcnt lgkmcnt(2)
	v_pk_add_f32 v[222:223], v[222:223], v[224:225]
	v_pk_add_f32 v[232:233], v[232:233], v[234:235]
	v_pk_add_f32 v[110:111], v[110:111], v[114:115]
	s_waitcnt lgkmcnt(0)
	v_pk_add_f32 v[236:237], v[236:237], v[238:239]
	v_pk_add_f32 v[226:227], v[226:227], v[228:229]
	v_pk_add_f32 v[222:223], v[222:223], v[232:233]
	v_pk_add_f32 v[102:103], v[102:103], v[110:111]
	v_pk_add_f32 v[236:237], v[236:237], v[226:227]
	s_add_i32 s87, s87, 1
	v_pk_add_f32 v[222:223], v[222:223], v[236:237]
	s_add_i32 s90, s90, s94
	v_pk_add_f32 v[102:103], v[102:103], v[222:223] op_sel:[0,1] op_sel_hi:[1,0]
	s_cmp_lt_u32 s87, 4
	v_cvt_pk_bf16_f32 v244, v102, v103
	s_nop 0
	global_store_dword v243, v244, s[88:89]
	s_waitcnt lgkmcnt(0)
	s_cbranch_scc1 .Lrw0_group

; __device__ __forceinline__ float sigm(float x) { return __builtin_amdgcn_rcpf(1.f + __expf(-x)); }
; template <int CTRL> __device__ __forceinline__ float dppf(float x) { return __builtin_bit_cast(float, __builtin_amdgcn_update_dpp(0, __builtin_bit_cast(int, x), CTRL, 0xF, 0xF, false)); }
; #define LDS_BAR() asm volatile("s_waitcnt lgkmcnt(0)\n\ts_barrier" ::: "memory")
; __device__ __forceinline__ void phase_rwkv_scan(const Fr& F, int jr) {
;     ...
;         for (int chunk = 0; chunk < TB / 64; ++chunk) {
; #pragma unroll
;             for (int hh = 0; hh < 2; ++hh) {
;                 const int hk = (ht0 + hh) * 16 + l15;
;                 f32x4 cw = {0.f, 0.f, 0.f, 0.f}, ca = {0.f, 0.f, 0.f, 0.f};
; #pragma unroll
;                 for (int kst = 0; kst < 2; ++kst) { cw = __builtin_amdgcn_mfma_f32_16x16x32_bf16(Aw[kst], Bw[hh][kst], cw, 0, 0, 0); ca = __builtin_amdgcn_mfma_f32_16x16x32_bf16(Aa[kst], Ba[hh][kst], ca, 0, 0, 0); }
; #pragma unroll
;                 for (int reg = 0; reg < 4; ++reg) { const int pp = pt * 16 + lq * 4 + reg;
;                     Wv[pp * 64 + hk] = __expf(-0.60653066f * sigm(w0v[hh] + cw[reg]));
;                     Av[pp * 64 + hk] = sigm(a0v[hh] + ca[reg]); }
;             }
;             LDS_BAR();
;             {
;                 const float kr[8] = {lo_bf(kw.x), hi_bf(kw.x), lo_bf(kw.y), hi_bf(kw.y), lo_bf(kw.z), hi_bf(kw.z), lo_bf(kw.w), hi_bf(kw.w)};
;                 const float rr[8] = {lo_bf(rw.x), hi_bf(rw.x), lo_bf(rw.y), hi_bf(rw.y), lo_bf(rw.z), hi_bf(rw.z), lo_bf(rw.w), hi_bf(rw.w)};
;                 float kq[8]; float ss = 0.f, bon = 0.f;
; #pragma unroll
;                 for (int i = 0; i < 8; ++i) { kq[i] = kr[i] * kkc[i]; ss += kq[i] * kq[i]; bon += rr[i] * kr[i] * rkc[i]; }
;                 ss += dppf<0xB1>(ss); ss += dppf<0x4E>(ss); ss += dppf<0x141>(ss); bon += dppf<0xB1>(bon); bon += dppf<0x4E>(bon); bon += dppf<0x141>(bon);
;                 if (s == 0 && half == 0 && j8 == 0) Bon[((size_t)b * TB + tokof(s, chunk * 64 + p2)) * 16 + h] = bon;
.LBB0_2534:
	s_cmp_eq_u32 s55, 0
	s_cbranch_scc1 .Lvw_rw3_all
	s_cmp_gt_u32 s68, 3
	s_cbranch_scc1 .Lvw_rw3_all
	s_waitcnt vmcnt(6)
	s_branch .Lvw_rw3_done
.Lvw_rw3_all:
	s_waitcnt vmcnt(2)
.Lvw_rw3_done:
	v_mfma_f32_16x16x32_bf16 v[80:83], v[56:59], v[0:3], 0
	v_lshlrev_b32_e32 v92, 16, v73
	v_and_b32_e32 v93, 0xffff0000, v73
	v_pk_mul_f32 v[98:99], v[46:47], v[92:93]
	v_mfma_f32_16x16x32_bf16 v[80:83], v[60:63], v[4:7], v[80:83]
	v_mul_f32_e64 v106, v98, v98
	v_mul_f32_e64 v107, v99, v99
	v_and_b32_e32 v91, 0xffff0000, v74
	v_and_b32_e32 v95, 0xffff0000, v75
	v_mfma_f32_16x16x32_bf16 v[84:87], v[64:67], v[8:11], 0
	v_mfma_f32_16x16x32_bf16 v[84:87], v[68:71], v[12:15], v[84:87]
	s_nop 1
	v_add_f32_e32 v80, v192, v80
	v_mul_f32_e32 v80, 0xbfb8aa3b, v80
	v_exp_f32_e32 v80, v80
	v_add_f32_e32 v81, v192, v81
	v_mul_f32_e32 v81, 0xbfb8aa3b, v81
	v_exp_f32_e32 v81, v81
	v_add_f32_e32 v80, 1.0, v80
	v_rcp_f32_e32 v80, v80
	v_add_f32_e32 v84, v193, v84
	v_add_f32_e32 v81, 1.0, v81
	v_rcp_f32_e32 v81, v81
	v_mul_f32_e32 v80, 0xbf1b4598, v80
	v_mul_f32_e32 v80, 0x3fb8aa3b, v80
	v_exp_f32_e32 v80, v80
	v_mul_f32_e32 v81, 0xbf1b4598, v81
	v_mul_f32_e32 v81, 0x3fb8aa3b, v81
	v_add_f32_e32 v83, v192, v83
	ds_write_b32 v177, v80
	v_exp_f32_e32 v80, v81
	v_add_f32_e32 v81, v192, v82
	v_mul_f32_e32 v81, 0xbfb8aa3b, v81
	v_add_f32_e32 v82, v193, v85
	v_exp_f32_e32 v81, v81
	v_mul_f32_e32 v82, 0xbfb8aa3b, v82
	v_exp_f32_e32 v82, v82
	v_mul_f32_e32 v84, 0xbfb8aa3b, v84
	v_add_f32_e32 v81, 1.0, v81
	v_mul_f32_e32 v83, 0xbfb8aa3b, v83
	v_exp_f32_e32 v84, v84
	v_rcp_f32_e32 v81, v81
	ds_write_b32 v177, v80 offset:256
	v_add_f32_e32 v80, 1.0, v82
	v_add_f32_e32 v82, v193, v86
	v_exp_f32_e32 v83, v83
	v_mul_f32_e32 v82, 0xbfb8aa3b, v82
	v_exp_f32_e32 v82, v82
	v_add_f32_e32 v84, 1.0, v84
	v_mul_f32_e32 v81, 0xbf1b4598, v81
	v_add_f32_e32 v83, 1.0, v83
	v_rcp_f32_e32 v84, v84
	v_rcp_f32_e32 v80, v80
	v_mul_f32_e32 v81, 0x3fb8aa3b, v81
	v_rcp_f32_e32 v83, v83
	v_exp_f32_e32 v81, v81
	v_add_f32_e32 v82, 1.0, v82
	v_rcp_f32_e32 v82, v82
	ds_write_b32 v178, v84
	ds_write_b32 v179, v80
	ds_write_b32 v177, v81 offset:512
	ds_write_b32 v180, v82
	v_mul_f32_e32 v80, 0xbf1b4598, v83
	v_mul_f32_e32 v80, 0x3fb8aa3b, v80
	v_exp_f32_e32 v88, v80
	v_mfma_f32_16x16x32_bf16 v[80:83], v[56:59], v[16:19], 0
	v_add_f32_e32 v84, v193, v87
	v_mul_f32_e32 v84, 0xbfb8aa3b, v84
	v_exp_f32_e32 v84, v84
	v_mfma_f32_16x16x32_bf16 v[80:83], v[60:63], v[20:23], v[80:83]
	v_add_f32_e32 v84, 1.0, v84
	v_rcp_f32_e32 v89, v84
	v_mfma_f32_16x16x32_bf16 v[84:87], v[64:67], v[24:27], 0
	s_nop 4
	v_add_f32_e32 v80, v195, v80
	v_mul_f32_e32 v80, 0xbfb8aa3b, v80
	v_exp_f32_e32 v80, v80
	v_mfma_f32_16x16x32_bf16 v[84:87], v[68:71], v[28:31], v[84:87]
	v_add_f32_e32 v81, v195, v81
	v_mul_f32_e32 v81, 0xbfb8aa3b, v81
	v_add_f32_e32 v80, 1.0, v80
	v_rcp_f32_e32 v80, v80
	v_exp_f32_e32 v81, v81
	s_nop 2
	v_add_f32_e32 v84, v194, v84
	v_mul_f32_e32 v84, 0xbfb8aa3b, v84
	v_mul_f32_e32 v80, 0xbf1b4598, v80
	v_mul_f32_e32 v80, 0x3fb8aa3b, v80
	v_exp_f32_e32 v80, v80
	v_exp_f32_e32 v84, v84
	v_add_f32_e32 v82, v195, v82
	v_add_f32_e32 v81, 1.0, v81
	v_mul_f32_e32 v82, 0xbfb8aa3b, v82
	ds_write_b32 v177, v88 offset:768
	ds_write_b32 v181, v89
	v_rcp_f32_e32 v81, v81
	ds_write_b32 v177, v80 offset:64
	v_add_f32_e32 v80, 1.0, v84
	v_add_f32_e32 v84, v194, v85
	v_exp_f32_e32 v82, v82
	v_mul_f32_e32 v84, 0xbfb8aa3b, v84
	v_exp_f32_e32 v84, v84
	v_mul_f32_e32 v81, 0xbf1b4598, v81
	v_add_f32_e32 v82, 1.0, v82
	v_rcp_f32_e32 v80, v80
	v_mul_f32_e32 v81, 0x3fb8aa3b, v81
	v_rcp_f32_e32 v82, v82
	v_exp_f32_e32 v81, v81
	v_add_f32_e32 v84, 1.0, v84
	v_rcp_f32_e32 v84, v84
	ds_write_b32 v182, v80
	ds_write_b32 v183, v81 offset:256
	ds_write_b32 v184, v84
	v_mul_f32_e32 v80, 0xbf1b4598, v82
	v_add_f32_e32 v82, v195, v83
	v_mul_f32_e32 v82, 0xbfb8aa3b, v82
	v_exp_f32_e32 v82, v82
	v_add_f32_e32 v81, v194, v86
	v_mul_f32_e32 v81, 0xbfb8aa3b, v81
	v_exp_f32_e32 v81, v81
	v_add_f32_e32 v82, 1.0, v82
	v_rcp_f32_e32 v82, v82
	v_add_f32_e32 v83, v194, v87
	v_mul_f32_e32 v83, 0xbfb8aa3b, v83
	v_exp_f32_e32 v83, v83
	v_mul_f32_e32 v80, 0x3fb8aa3b, v80
	s_waitcnt vmcnt(1)
	v_lshlrev_b32_e32 v84, 16, v76
	v_lshlrev_b32_e32 v88, 16, v72
	v_exp_f32_e32 v80, v80
	v_add_f32_e32 v81, 1.0, v81
	v_mul_f32_e32 v82, 0xbf1b4598, v82
	v_and_b32_e32 v85, 0xffff0000, v76
	v_and_b32_e32 v89, 0xffff0000, v72
	v_mul_f32_e32 v90, v88, v84
	v_rcp_f32_e32 v81, v81
	v_mul_f32_e32 v82, 0x3fb8aa3b, v82
	v_lshlrev_b32_e32 v86, 16, v77
	v_fma_f32 v112, v32, v90, 0
	v_mul_f32_e32 v90, v89, v85
	v_exp_f32_e32 v82, v82
	v_add_f32_e32 v83, 1.0, v83
	v_and_b32_e32 v87, 0xffff0000, v77
	v_fmac_f32_e32 v112, v33, v90
	v_mul_f32_e32 v90, v92, v86
	v_rcp_f32_e32 v83, v83
	v_pk_mul_f32 v[96:97], v[44:45], v[88:89]
	v_fmac_f32_e32 v112, v34, v90
	v_mul_f32_e32 v90, v93, v87
	ds_write_b32 v183, v80 offset:512
	ds_write_b32 v185, v81
	ds_write_b32 v183, v82 offset:768
	ds_write_b32 v186, v83
	v_lshlrev_b32_e32 v80, 16, v78
	v_pk_mul_f32 v[104:105], v[96:97], v[96:97]
	v_fmac_f32_e32 v112, v35, v90
	v_lshlrev_b32_e32 v90, 16, v74
	v_and_b32_e32 v81, 0xffff0000, v78
	v_mul_f32_e32 v94, v90, v80
	v_add_f32_e32 v104, v104, v105
	v_pk_mul_f32 v[100:101], v[40:41], v[90:91]
	v_fmac_f32_e32 v112, v36, v94
	v_mul_f32_e32 v94, v91, v81
	v_add_f32_e32 v104, v106, v104
	v_pk_mul_f32 v[108:109], v[100:101], v[100:101]
	v_fmac_f32_e32 v112, v37, v94
	v_lshlrev_b32_e32 v94, 16, v75
	v_add_f32_e32 v104, v107, v104
	v_lshlrev_b32_e32 v82, 16, v79
	v_pk_mul_f32 v[102:103], v[42:43], v[94:95]
	v_add_f32_e32 v104, v108, v104
	v_and_b32_e32 v83, 0xffff0000, v79
	v_pk_mul_f32 v[110:111], v[102:103], v[102:103]
	v_mul_f32_e32 v113, v94, v82
	v_add_f32_e32 v104, v109, v104
	v_fmac_f32_e32 v112, v38, v113
	v_add_f32_e32 v104, v110, v104
	v_mul_f32_e32 v105, v95, v83
	v_add_f32_e32 v104, v111, v104
	v_fmac_f32_e32 v112, v39, v105
	s_waitcnt lgkmcnt(0)
	s_barrier
	v_mov_b32_e32 v105, 0
	v_add_f32_dpp v104, v104, v104 quad_perm:[1,0,3,2] row_mask:0xf bank_mask:0xf bound_ctrl:1
	v_add_f32_dpp v106, v112, v112 quad_perm:[1,0,3,2] row_mask:0xf bank_mask:0xf bound_ctrl:1
	v_mov_b32_e32 v107, 0
	v_add_f32_dpp v104, v104, v104 quad_perm:[2,3,0,1] row_mask:0xf bank_mask:0xf bound_ctrl:1
	v_add_f32_dpp v106, v106, v106 quad_perm:[2,3,0,1] row_mask:0xf bank_mask:0xf bound_ctrl:1
	s_nop 0
	v_mov_b32_dpp v105, v104 row_half_mirror row_mask:0xf bank_mask:0xf
	v_mov_b32_dpp v107, v106 row_half_mirror row_mask:0xf bank_mask:0xf
	s_and_saveexec_b64 s[10:11], s[8:9]
	s_cbranch_execz .LBB0_2536
	v_lshl_add_u32 v122, s55, 6, v145
	v_add_f32_e32 v108, v106, v107
	v_lshlrev_b64 v[106:107], 6, v[122:123]
	v_lshl_add_u64 v[106:107], s[44:45], 0, v[106:107]
	global_store_dword v[106:107], v108, off

; __global__ void __launch_bounds__(NTHR) fwd_kernel(Args args) {
;     extern __shared__ __attribute__((aligned(16))) unsigned char lds[];
;     cg::grid_group grid = cg::this_grid();
;     Fr F; F.a = &args; F.lds = lds; F.ws = args.ws; F.tid = threadIdx.x; F.lane = F.tid & 63; F.wave = __builtin_amdgcn_readfirstlane(F.tid >> 6); F.gw = blockIdx.x * NWAVES + F.wave;
	.amdhsa_kernel _Z10fwd_kernel4Args
		.amdhsa_group_segment_fixed_size 0
		.amdhsa_private_segment_fixed_size 0
		.amdhsa_kernarg_size 584
		.amdhsa_user_sgpr_count 2
		.amdhsa_user_sgpr_dispatch_ptr 0
		.amdhsa_user_sgpr_queue_ptr 0
		.amdhsa_user_sgpr_kernarg_segment_ptr 1
		.amdhsa_user_sgpr_dispatch_id 0
		.amdhsa_user_sgpr_kernarg_preload_length 0
		.amdhsa_user_sgpr_kernarg_preload_offset 0
		.amdhsa_user_sgpr_private_segment_size 0
		.amdhsa_uses_dynamic_stack 0
		.amdhsa_enable_private_segment 0
		.amdhsa_system_sgpr_workgroup_id_x 1
		.amdhsa_system_sgpr_workgroup_id_y 0
		.amdhsa_system_sgpr_workgroup_id_z 0
		.amdhsa_system_sgpr_workgroup_info 0
		.amdhsa_system_vgpr_workitem_id 2
		.amdhsa_next_free_vgpr 246
		.amdhsa_next_free_sgpr 97
		.amdhsa_accum_offset 248
		.amdhsa_reserve_vcc 1
		.amdhsa_float_round_mode_32 0
		.amdhsa_float_round_mode_16_64 0
		.amdhsa_float_denorm_mode_32 3
		.amdhsa_float_denorm_mode_16_64 3
		.amdhsa_dx10_clamp 1
		.amdhsa_ieee_mode 1
		.amdhsa_fp16_overflow 0
		.amdhsa_tg_split 0
		.amdhsa_exception_fp_ieee_invalid_op 0
		.amdhsa_exception_fp_denorm_src 0
		.amdhsa_exception_fp_ieee_div_zero 0
		.amdhsa_exception_fp_ieee_overflow 0
		.amdhsa_exception_fp_ieee_underflow 0
		.amdhsa_exception_fp_ieee_inexact 0
		.amdhsa_exception_int_div_zero 0
	.end_amdhsa_kernel

; __global__ void __launch_bounds__(NTHR) fwd_kernel(Args args) {
;     extern __shared__ __attribute__((aligned(16))) unsigned char lds[];
;     cg::grid_group grid = cg::this_grid();
;     Fr F; F.a = &args; F.lds = lds; F.ws = args.ws; F.tid = threadIdx.x; F.lane = F.tid & 63; F.wave = __builtin_amdgcn_readfirstlane(F.tid >> 6); F.gw = blockIdx.x * NWAVES + F.wave;
amdhsa.kernels:
  - .agpr_count:     0
    .args:
      - .offset:         0
        .size:           328
        .value_kind:     by_value
      - .offset:         328
        .size:           4
        .value_kind:     hidden_block_count_x
      - .offset:         332
        .size:           4
        .value_kind:     hidden_block_count_y
      - .offset:         336
        .size:           4
        .value_kind:     hidden_block_count_z
      - .offset:         340
        .size:           2
        .value_kind:     hidden_group_size_x
      - .offset:         342
        .size:           2
        .value_kind:     hidden_group_size_y
      - .offset:         344
        .size:           2
        .value_kind:     hidden_group_size_z
      - .offset:         346
        .size:           2
        .value_kind:     hidden_remainder_x
      - .offset:         348
        .size:           2
        .value_kind:     hidden_remainder_y
      - .offset:         350
        .size:           2
        .value_kind:     hidden_remainder_z
      - .offset:         368
        .size:           8
        .value_kind:     hidden_global_offset_x
      - .offset:         376
        .size:           8
        .value_kind:     hidden_global_offset_y
      - .offset:         384
        .size:           8
        .value_kind:     hidden_global_offset_z
      - .offset:         392
        .size:           2
        .value_kind:     hidden_grid_dims
      - .offset:         416
        .size:           8
        .value_kind:     hidden_multigrid_sync_arg
      - .offset:         448
        .size:           4
        .value_kind:     hidden_dynamic_lds_size
    .group_segment_fixed_size: 0
    .kernarg_segment_align: 8
    .kernarg_segment_size: 584
    .language:       OpenCL C
    .language_version:
      - 2
      - 0
    .max_flat_workgroup_size: 512
    .name:           _Z10fwd_kernel4Args
    .private_segment_fixed_size: 0
    .sgpr_count:     103
    .sgpr_spill_count: 0
    .symbol:         _Z10fwd_kernel4Args.kd
    .uniform_work_group_size: 1
    .uses_dynamic_stack: false
    .vgpr_count:     246
    .vgpr_spill_count: 0
    .wavefront_size: 64
